# v051_poolprio
# speedup vs baseline: 1.0035x; 1.0035x over previous
; __device__ __forceinline__ float bflo(unsigned u) { return __uint_as_float(u << 16); }
; __device__ __forceinline__ float bfhi(unsigned u) { return __uint_as_float(u & 0xffff0000u); }
; #define SCHED __builtin_amdgcn_sched_barrier(0)
; template <int W>
; __device__ __forceinline__ void pool_compute(const Params& p, int layer, int g, int dh, int tt, const int tidx) {
;   const int lane = tidx & 63, n = lane & 31, half = lane >> 5;
;   const int t = tt * 32 + n, pos = t & (SEQ - 1);
;   const int cnt = min(pos + 1, W);
;   const float inv = 1.f / (float)cnt;
;   const char* wpb = (const char*)(p.ws + WS_WPOOL + (size_t)layer * SZ_WPOOL) + (size_t)g * 131072;
;   u16* yraw = (u16*)(p.ws + WS_YRAW);
;   const float* psc = p.pool_scale + layer * 1024 + g * 256;
;   const char* xl = smem + g * (PROWS * PXS) + (15 + n) * PXS + half * 16;
;   const unsigned woff = (unsigned)(n * 512 + half * 16);
;   f32x16 acc[4];
; #pragma unroll
;   for (int d = 0; d < 4; ++d)
; #pragma unroll
;     for (int i = 0; i < 16; ++i) acc[d][i] = 0.f;
; #pragma unroll 1
;   for (int kb = 0; kb < 4; ++kb) {
;     u32x4 av[4][4];
; #pragma unroll
;     for (int k4 = 0; k4 < 4; ++k4)
; #pragma unroll
;       for (int d = 0; d < 4; ++d)
;         av[k4][d] = *reinterpret_cast<const u32x4*>(wpb + (woff + (unsigned)(((dh * 4 + d) * 32) * 512 + (kb * 4 + k4) * 32)));
;     SCHED;
; #pragma unroll
;     for (int k4 = 0; k4 < 4; ++k4) {
;       const int ks = kb * 4 + k4;
;       float sum[8];
; #pragma unroll
;       for (int j = 0; j < 8; ++j) sum[j] = 0.f;
;       u32x4 x0 = *reinterpret_cast<const u32x4*>(xl + ks * 32);
; #pragma unroll
;       for (int i = 0; i < W; ++i) {
;         u32x4 xv = *reinterpret_cast<const u32x4*>(xl + ks * 32 - i * PXS);
;         sum[0] += bflo(xv.x); sum[1] += bfhi(xv.x); sum[2] += bflo(xv.y); sum[3] += bfhi(xv.y);
;         sum[4] += bflo(xv.z); sum[5] += bfhi(xv.z); sum[6] += bflo(xv.w); sum[7] += bfhi(xv.w);
;       }
.LBB0_178:
	v_cmp_eq_u32_e32 vcc, 2, v2
	s_mov_b64 s[14:15], -1
	s_and_saveexec_b64 s[12:13], vcc
	s_cbranch_execz .LBB0_182
	s_setprio 1
	v_min_u32_e32 v0, 7, v142
	v_add_u32_e32 v0, 1, v0
	v_cvt_f32_ubyte0_e32 v0, v0
	v_div_scale_f32 v1, s[14:15], v0, v0, 1.0
	v_rcp_f32_e32 v2, v1
	v_div_scale_f32 v3, vcc, 1.0, v0, 1.0
	v_readlane_b32 s14, v254, 13
	v_fma_f32 v4, -v1, v2, 1.0
	v_fmac_f32_e32 v2, v4, v2
	v_mul_f32_e32 v4, v3, v2
	v_fma_f32 v5, -v1, v4, v3
	v_fmac_f32_e32 v4, v5, v2
	v_fma_f32 v1, -v1, v4, v3
	v_div_fmas_f32 v1, v1, v2, v4
	v_add3_u32 v162, v144, v143, v134
	v_mov_b32_e32 v48, 0
	v_div_fixup_f32 v135, v1, v0, 1.0
	v_add3_u32 v145, v141, v134, s14
	v_lshl_add_u64 v[136:137], s[72:73], 0, v[162:163]
	s_mov_b64 s[14:15], 0
	v_mov_b32_e32 v49, v48
	v_mov_b32_e32 v50, v48
	v_mov_b32_e32 v51, v48
	v_mov_b32_e32 v52, v48
	v_mov_b32_e32 v53, v48
	v_mov_b32_e32 v54, v48
	v_mov_b32_e32 v55, v48
	v_mov_b32_e32 v56, v48
	v_mov_b32_e32 v57, v48
	v_mov_b32_e32 v58, v48
	v_mov_b32_e32 v59, v48
	v_mov_b32_e32 v60, v48
	v_mov_b32_e32 v61, v48
	v_mov_b32_e32 v62, v48
	v_mov_b32_e32 v63, v48
	v_mov_b32_e32 v32, v48
	v_mov_b32_e32 v33, v48
	v_mov_b32_e32 v34, v48
	v_mov_b32_e32 v35, v48
	v_mov_b32_e32 v36, v48
	v_mov_b32_e32 v37, v48
	v_mov_b32_e32 v38, v48
	v_mov_b32_e32 v39, v48
	v_mov_b32_e32 v40, v48
	v_mov_b32_e32 v41, v48
	v_mov_b32_e32 v42, v48
	v_mov_b32_e32 v43, v48
	v_mov_b32_e32 v44, v48
	v_mov_b32_e32 v45, v48
	v_mov_b32_e32 v46, v48
	v_mov_b32_e32 v47, v48
	v_mov_b32_e32 v16, v48
	v_mov_b32_e32 v17, v48
	v_mov_b32_e32 v18, v48
	v_mov_b32_e32 v19, v48
	v_mov_b32_e32 v20, v48
	v_mov_b32_e32 v21, v48
	v_mov_b32_e32 v22, v48
	v_mov_b32_e32 v23, v48
	v_mov_b32_e32 v24, v48
	v_mov_b32_e32 v25, v48
	v_mov_b32_e32 v26, v48
	v_mov_b32_e32 v27, v48
	v_mov_b32_e32 v28, v48
	v_mov_b32_e32 v29, v48
	v_mov_b32_e32 v30, v48
	v_mov_b32_e32 v31, v48
	v_mov_b32_e32 v0, v48
	v_mov_b32_e32 v1, v48
	v_mov_b32_e32 v2, v48
	v_mov_b32_e32 v3, v48
	v_mov_b32_e32 v4, v48
	v_mov_b32_e32 v5, v48
	v_mov_b32_e32 v6, v48
	v_mov_b32_e32 v7, v48
	v_mov_b32_e32 v8, v48
	v_mov_b32_e32 v9, v48
	v_mov_b32_e32 v10, v48
	v_mov_b32_e32 v11, v48
	v_mov_b32_e32 v12, v48
	v_mov_b32_e32 v13, v48
	v_mov_b32_e32 v14, v48
	v_mov_b32_e32 v15, v48
.LBB0_180:
	v_lshl_add_u64 v[64:65], v[136:137], 0, s[14:15]
	s_mov_b32 s16, 0x10840000
	v_add_co_u32_e32 v66, vcc, s16, v64
	s_mov_b32 s16, 0x10844000
	s_nop 0
	v_addc_co_u32_e32 v67, vcc, 0, v65, vcc
	v_add_co_u32_e32 v68, vcc, s16, v64
	s_mov_b32 s16, 0x10848000
	s_nop 0
	v_addc_co_u32_e32 v69, vcc, 0, v65, vcc
	v_add_co_u32_e32 v72, vcc, s16, v64
	s_mov_b32 s16, 0x1084c000
	s_nop 0
	v_addc_co_u32_e32 v73, vcc, 0, v65, vcc
	v_add_co_u32_e32 v76, vcc, s16, v64
	s_nop 1
	v_addc_co_u32_e32 v77, vcc, 0, v65, vcc
	global_load_dwordx4 v[118:121], v[66:67], off
	global_load_dwordx4 v[98:101], v[66:67], off offset:32
	global_load_dwordx4 v[122:125], v[68:69], off
	global_load_dwordx4 v[102:105], v[68:69], off offset:32
	global_load_dwordx4 v[126:129], v[72:73], off
	global_load_dwordx4 v[106:109], v[72:73], off offset:32
	global_load_dwordx4 v[130:133], v[76:77], off
	global_load_dwordx4 v[110:113], v[76:77], off offset:32
	global_load_dwordx4 v[80:83], v[66:67], off offset:64
	s_nop 0
	global_load_dwordx4 v[64:67], v[66:67], off offset:96
	s_nop 0
	global_load_dwordx4 v[84:87], v[68:69], off offset:64
	s_nop 0
	global_load_dwordx4 v[68:71], v[68:69], off offset:96
	s_nop 0
	global_load_dwordx4 v[88:91], v[72:73], off offset:64
	s_nop 0
	global_load_dwordx4 v[72:75], v[72:73], off offset:96
	s_nop 0
	global_load_dwordx4 v[92:95], v[76:77], off offset:64
	s_nop 0
	global_load_dwordx4 v[76:79], v[76:77], off offset:96
	ds_read_b128 v[114:117], v145 offset:3696
	s_add_u32 s14, s14, 0x80
	s_addc_u32 s15, s15, 0
	s_cmpk_lg_i32 s14, 0x200
	s_waitcnt lgkmcnt(0)
	v_lshlrev_b32_e32 v146, 16, v114
	v_and_b32_e32 v147, 0xffff0000, v114
	v_lshlrev_b32_e32 v148, 16, v115
	v_and_b32_e32 v149, 0xffff0000, v115
	v_lshlrev_b32_e32 v150, 16, v116
	v_and_b32_e32 v151, 0xffff0000, v116
	v_lshlrev_b32_e32 v152, 16, v117
	v_and_b32_e32 v153, 0xffff0000, v117
	ds_read_b128 v[114:117], v145 offset:3168
	v_add_f32_e32 v155, 0, v147
	v_add_f32_e32 v156, 0, v148
	v_add_f32_e32 v157, 0, v149
	v_add_f32_e32 v158, 0, v150
	s_waitcnt lgkmcnt(0)
	v_lshlrev_b32_e32 v162, 16, v114
	v_and_b32_e32 v114, 0xffff0000, v114
	v_add_f32_e32 v155, v155, v114
	v_lshlrev_b32_e32 v114, 16, v115
	v_add_f32_e32 v156, v156, v114
	v_and_b32_e32 v114, 0xffff0000, v115
	v_add_f32_e32 v157, v157, v114
	v_lshlrev_b32_e32 v114, 16, v116
	v_add_f32_e32 v159, 0, v151
	v_add_f32_e32 v158, v158, v114
	v_and_b32_e32 v114, 0xffff0000, v116
	v_add_f32_e32 v160, 0, v152
	v_add_f32_e32 v159, v159, v114
	v_lshlrev_b32_e32 v114, 16, v117
	v_add_f32_e32 v161, 0, v153
	v_add_f32_e32 v160, v160, v114
	v_and_b32_e32 v114, 0xffff0000, v117
	v_add_f32_e32 v161, v161, v114
	ds_read_b128 v[114:117], v145 offset:2640
	v_add_f32_e32 v154, 0, v146
	v_add_f32_e32 v154, v154, v162
	s_waitcnt lgkmcnt(0)
	v_lshlrev_b32_e32 v162, 16, v114
	v_and_b32_e32 v114, 0xffff0000, v114
	v_add_f32_e32 v155, v155, v114
	v_lshlrev_b32_e32 v114, 16, v115
	v_add_f32_e32 v156, v156, v114
	v_and_b32_e32 v114, 0xffff0000, v115
	v_add_f32_e32 v157, v157, v114
	v_lshlrev_b32_e32 v114, 16, v116
	v_add_f32_e32 v158, v158, v114
	v_and_b32_e32 v114, 0xffff0000, v116
	v_add_f32_e32 v159, v159, v114
	v_lshlrev_b32_e32 v114, 16, v117
	v_add_f32_e32 v160, v160, v114
	v_and_b32_e32 v114, 0xffff0000, v117
	v_add_f32_e32 v161, v161, v114
	ds_read_b128 v[114:117], v145 offset:2112
	v_add_f32_e32 v154, v154, v162
	s_waitcnt lgkmcnt(0)
; __device__ __forceinline__ float bflo(unsigned u) { return __uint_as_float(u << 16); }
; __device__ __forceinline__ float bfhi(unsigned u) { return __uint_as_float(u & 0xffff0000u); }
; template <int W>
; __device__ __forceinline__ void pool_compute(const Params& p, int layer, int g, int dh, int tt, const int tidx) {
;     ...
;     for (int k4 = 0; k4 < 4; ++k4) {
;       const int ks = kb * 4 + k4;
;       float sum[8];
; #pragma unroll
;       for (int j = 0; j < 8; ++j) sum[j] = 0.f;
;       u32x4 x0 = *reinterpret_cast<const u32x4*>(xl + ks * 32);
; #pragma unroll
;       for (int i = 0; i < W; ++i) {
;         u32x4 xv = *reinterpret_cast<const u32x4*>(xl + ks * 32 - i * PXS);
;         sum[0] += bflo(xv.x); sum[1] += bfhi(xv.x); sum[2] += bflo(xv.y); sum[3] += bfhi(xv.y);
;         sum[4] += bflo(xv.z); sum[5] += bfhi(xv.z); sum[6] += bflo(xv.w); sum[7] += bfhi(xv.w);
;       }
;       u32x4 bfr;
;       bfr.x = pack2(sum[0] * inv - bflo(x0.x), sum[1] * inv - bfhi(x0.x));
;       bfr.y = pack2(sum[2] * inv - bflo(x0.y), sum[3] * inv - bfhi(x0.y));
;       bfr.z = pack2(sum[4] * inv - bflo(x0.z), sum[5] * inv - bfhi(x0.z));
;       bfr.w = pack2(sum[6] * inv - bflo(x0.w), sum[7] * inv - bfhi(x0.w));
; #pragma unroll
;       for (int d = 0; d < 4; ++d) acc[d] = __builtin_amdgcn_mfma_f32_32x32x16_bf16(as_bf16x8(av[k4][d]), as_bf16x8(bfr), acc[d], 0, 0, 0);
;     }
	v_lshlrev_b32_e32 v162, 16, v114
	v_and_b32_e32 v114, 0xffff0000, v114
	v_add_f32_e32 v155, v155, v114
	v_lshlrev_b32_e32 v114, 16, v115
	v_add_f32_e32 v156, v156, v114
	v_and_b32_e32 v114, 0xffff0000, v115
	v_add_f32_e32 v157, v157, v114
	v_lshlrev_b32_e32 v114, 16, v116
	v_add_f32_e32 v158, v158, v114
	v_and_b32_e32 v114, 0xffff0000, v116
	v_add_f32_e32 v159, v159, v114
	v_lshlrev_b32_e32 v114, 16, v117
	v_add_f32_e32 v160, v160, v114
	v_and_b32_e32 v114, 0xffff0000, v117
	v_add_f32_e32 v161, v161, v114
	ds_read_b128 v[114:117], v145 offset:1584
	v_add_f32_e32 v154, v154, v162
	s_waitcnt lgkmcnt(0)
	v_lshlrev_b32_e32 v162, 16, v114
	v_and_b32_e32 v114, 0xffff0000, v114
	v_add_f32_e32 v155, v155, v114
	v_lshlrev_b32_e32 v114, 16, v115
	v_add_f32_e32 v156, v156, v114
	v_and_b32_e32 v114, 0xffff0000, v115
	v_add_f32_e32 v157, v157, v114
	v_lshlrev_b32_e32 v114, 16, v116
	v_add_f32_e32 v158, v158, v114
	v_and_b32_e32 v114, 0xffff0000, v116
	v_add_f32_e32 v159, v159, v114
	v_lshlrev_b32_e32 v114, 16, v117
	v_add_f32_e32 v160, v160, v114
	v_and_b32_e32 v114, 0xffff0000, v117
	v_add_f32_e32 v161, v161, v114
	ds_read_b128 v[114:117], v145 offset:1056
	v_add_f32_e32 v154, v154, v162
	s_waitcnt lgkmcnt(0)
	v_lshlrev_b32_e32 v162, 16, v114
	v_and_b32_e32 v114, 0xffff0000, v114
	v_add_f32_e32 v155, v155, v114
	v_lshlrev_b32_e32 v114, 16, v115
	v_add_f32_e32 v156, v156, v114
	v_and_b32_e32 v114, 0xffff0000, v115
	v_add_f32_e32 v157, v157, v114
	v_lshlrev_b32_e32 v114, 16, v116
	v_add_f32_e32 v158, v158, v114
	v_and_b32_e32 v114, 0xffff0000, v116
	v_add_f32_e32 v159, v159, v114
	v_lshlrev_b32_e32 v114, 16, v117
	v_add_f32_e32 v160, v160, v114
	v_and_b32_e32 v114, 0xffff0000, v117
	v_add_f32_e32 v161, v161, v114
	ds_read_b128 v[114:117], v145 offset:528
	v_add_f32_e32 v154, v154, v162
	s_waitcnt lgkmcnt(0)
	v_lshlrev_b32_e32 v162, 16, v114
	v_and_b32_e32 v114, 0xffff0000, v114
	v_add_f32_e32 v165, v155, v114
	v_lshlrev_b32_e32 v114, 16, v115
	v_add_f32_e32 v166, v156, v114
	v_and_b32_e32 v114, 0xffff0000, v115
	v_add_f32_e32 v167, v157, v114
	v_lshlrev_b32_e32 v114, 16, v116
	v_add_f32_e32 v158, v158, v114
	v_and_b32_e32 v114, 0xffff0000, v116
	v_add_f32_e32 v159, v159, v114
	v_lshlrev_b32_e32 v114, 16, v117
	v_add_f32_e32 v160, v160, v114
	v_and_b32_e32 v114, 0xffff0000, v117
	v_add_f32_e32 v162, v154, v162
	v_add_f32_e32 v161, v161, v114
	ds_read_b128 v[154:157], v145
	ds_read_b128 v[114:117], v145 offset:32
	s_waitcnt lgkmcnt(1)
	v_lshlrev_b32_e32 v168, 16, v154
	v_and_b32_e32 v154, 0xffff0000, v154
	v_add_f32_e32 v162, v162, v168
	v_add_f32_e32 v154, v165, v154
	v_lshlrev_b32_e32 v165, 16, v155
	v_and_b32_e32 v155, 0xffff0000, v155
	v_add_f32_e32 v165, v166, v165
	v_add_f32_e32 v155, v167, v155
	v_lshlrev_b32_e32 v166, 16, v156
	v_and_b32_e32 v156, 0xffff0000, v156
	v_fma_f32 v146, v135, v162, -v146
	v_fma_f32 v147, v135, v154, -v147
	v_add_f32_e32 v158, v158, v166
	v_add_f32_e32 v156, v159, v156
	v_lshlrev_b32_e32 v159, 16, v157
	v_cvt_pk_bf16_f32 v146, v146, v147
	v_fma_f32 v147, v135, v165, -v148
	v_fma_f32 v148, v135, v155, -v149
	v_add_f32_e32 v159, v160, v159
	v_and_b32_e32 v157, 0xffff0000, v157
	v_cvt_pk_bf16_f32 v147, v147, v148
	v_fma_f32 v148, v135, v158, -v150
	v_fma_f32 v149, v135, v156, -v151
	v_add_f32_e32 v157, v161, v157
	v_cvt_pk_bf16_f32 v148, v148, v149
	v_fma_f32 v149, v135, v159, -v152
	v_fma_f32 v150, v135, v157, -v153
	v_cvt_pk_bf16_f32 v149, v149, v150
	s_waitcnt vmcnt(15)
	v_mfma_f32_32x32x16_bf16 v[48:63], v[118:121], v[146:149], v[48:63]
	ds_read_b128 v[118:121], v145 offset:3728
	s_waitcnt vmcnt(13)
	v_mfma_f32_32x32x16_bf16 v[32:47], v[122:125], v[146:149], v[32:47]
	s_waitcnt lgkmcnt(0)
	v_lshlrev_b32_e32 v122, 16, v118
	v_and_b32_e32 v123, 0xffff0000, v118
	v_lshlrev_b32_e32 v124, 16, v119
	v_and_b32_e32 v125, 0xffff0000, v119
	s_waitcnt vmcnt(11)
	v_mfma_f32_32x32x16_bf16 v[16:31], v[126:129], v[146:149], v[16:31]
	v_lshlrev_b32_e32 v126, 16, v120
	v_and_b32_e32 v127, 0xffff0000, v120
	v_lshlrev_b32_e32 v128, 16, v121
	v_and_b32_e32 v129, 0xffff0000, v121
	ds_read_b128 v[118:121], v145 offset:3200
	s_waitcnt lgkmcnt(0)
	v_lshlrev_b32_e32 v150, 16, v118
	s_waitcnt vmcnt(9)
	v_mfma_f32_32x32x16_bf16 v[0:15], v[130:133], v[146:149], v[0:15]
	v_add_f32_e32 v131, 0, v123
	v_and_b32_e32 v118, 0xffff0000, v118
	v_add_f32_e32 v132, 0, v124
	v_add_f32_e32 v131, v131, v118
	v_lshlrev_b32_e32 v118, 16, v119
	v_add_f32_e32 v133, 0, v125
	v_add_f32_e32 v132, v132, v118
	v_and_b32_e32 v118, 0xffff0000, v119
	v_add_f32_e32 v146, 0, v126
	v_add_f32_e32 v133, v133, v118
	v_lshlrev_b32_e32 v118, 16, v120
	v_add_f32_e32 v147, 0, v127
	v_add_f32_e32 v146, v146, v118
	v_and_b32_e32 v118, 0xffff0000, v120
	v_add_f32_e32 v148, 0, v128
	v_add_f32_e32 v147, v147, v118
	v_lshlrev_b32_e32 v118, 16, v121
	v_add_f32_e32 v149, 0, v129
	v_add_f32_e32 v148, v148, v118
	v_and_b32_e32 v118, 0xffff0000, v121
	v_add_f32_e32 v149, v149, v118
	ds_read_b128 v[118:121], v145 offset:2672
	v_add_f32_e32 v130, 0, v122
	v_add_f32_e32 v130, v130, v150
	s_waitcnt lgkmcnt(0)
	v_lshlrev_b32_e32 v150, 16, v118
	v_and_b32_e32 v118, 0xffff0000, v118
	v_add_f32_e32 v131, v131, v118
	v_lshlrev_b32_e32 v118, 16, v119
	v_add_f32_e32 v132, v132, v118
	v_and_b32_e32 v118, 0xffff0000, v119
	v_add_f32_e32 v133, v133, v118
	v_lshlrev_b32_e32 v118, 16, v120
	v_add_f32_e32 v146, v146, v118
	v_and_b32_e32 v118, 0xffff0000, v120
	v_add_f32_e32 v147, v147, v118
	v_lshlrev_b32_e32 v118, 16, v121
	v_add_f32_e32 v148, v148, v118
	v_and_b32_e32 v118, 0xffff0000, v121
	v_add_f32_e32 v149, v149, v118
	ds_read_b128 v[118:121], v145 offset:2144
	v_add_f32_e32 v130, v130, v150
	s_waitcnt lgkmcnt(0)
; __device__ __forceinline__ float bflo(unsigned u) { return __uint_as_float(u << 16); }
; __device__ __forceinline__ float bfhi(unsigned u) { return __uint_as_float(u & 0xffff0000u); }
; template <int W>
; __device__ __forceinline__ void pool_compute(const Params& p, int layer, int g, int dh, int tt, const int tidx) {
;     ...
;     for (int k4 = 0; k4 < 4; ++k4) {
;       const int ks = kb * 4 + k4;
;       float sum[8];
; #pragma unroll
;       for (int j = 0; j < 8; ++j) sum[j] = 0.f;
;       u32x4 x0 = *reinterpret_cast<const u32x4*>(xl + ks * 32);
; #pragma unroll
;       for (int i = 0; i < W; ++i) {
;         u32x4 xv = *reinterpret_cast<const u32x4*>(xl + ks * 32 - i * PXS);
;         sum[0] += bflo(xv.x); sum[1] += bfhi(xv.x); sum[2] += bflo(xv.y); sum[3] += bfhi(xv.y);
;         sum[4] += bflo(xv.z); sum[5] += bfhi(xv.z); sum[6] += bflo(xv.w); sum[7] += bfhi(xv.w);
;       }
;       u32x4 bfr;
;       bfr.x = pack2(sum[0] * inv - bflo(x0.x), sum[1] * inv - bfhi(x0.x));
;       bfr.y = pack2(sum[2] * inv - bflo(x0.y), sum[3] * inv - bfhi(x0.y));
;       bfr.z = pack2(sum[4] * inv - bflo(x0.z), sum[5] * inv - bfhi(x0.z));
;       bfr.w = pack2(sum[6] * inv - bflo(x0.w), sum[7] * inv - bfhi(x0.w));
; #pragma unroll
;       for (int d = 0; d < 4; ++d) acc[d] = __builtin_amdgcn_mfma_f32_32x32x16_bf16(as_bf16x8(av[k4][d]), as_bf16x8(bfr), acc[d], 0, 0, 0);
;     }
	v_lshlrev_b32_e32 v150, 16, v118
	v_and_b32_e32 v118, 0xffff0000, v118
	v_add_f32_e32 v131, v131, v118
	v_lshlrev_b32_e32 v118, 16, v119
	v_add_f32_e32 v132, v132, v118
	v_and_b32_e32 v118, 0xffff0000, v119
	v_add_f32_e32 v133, v133, v118
	v_lshlrev_b32_e32 v118, 16, v120
	v_add_f32_e32 v146, v146, v118
	v_and_b32_e32 v118, 0xffff0000, v120
	v_add_f32_e32 v147, v147, v118
	v_lshlrev_b32_e32 v118, 16, v121
	v_add_f32_e32 v148, v148, v118
	v_and_b32_e32 v118, 0xffff0000, v121
	v_add_f32_e32 v149, v149, v118
	ds_read_b128 v[118:121], v145 offset:1616
	v_add_f32_e32 v130, v130, v150
	s_waitcnt lgkmcnt(0)
	v_lshlrev_b32_e32 v150, 16, v118
	v_and_b32_e32 v118, 0xffff0000, v118
	v_add_f32_e32 v131, v131, v118
	v_lshlrev_b32_e32 v118, 16, v119
	v_add_f32_e32 v132, v132, v118
	v_and_b32_e32 v118, 0xffff0000, v119
	v_add_f32_e32 v133, v133, v118
	v_lshlrev_b32_e32 v118, 16, v120
	v_add_f32_e32 v130, v130, v150
	v_add_f32_e32 v150, v146, v118
	v_and_b32_e32 v118, 0xffff0000, v120
	v_add_f32_e32 v151, v147, v118
	v_lshlrev_b32_e32 v118, 16, v121
	v_add_f32_e32 v152, v148, v118
	v_and_b32_e32 v118, 0xffff0000, v121
	v_add_f32_e32 v153, v149, v118
	ds_read_b128 v[118:121], v145 offset:1088
	s_waitcnt lgkmcnt(0)
	v_lshlrev_b32_e32 v146, 16, v118
	v_and_b32_e32 v118, 0xffff0000, v118
	v_add_f32_e32 v148, v131, v118
	v_lshlrev_b32_e32 v118, 16, v119
	v_add_f32_e32 v147, v132, v118
	v_and_b32_e32 v118, 0xffff0000, v119
	v_add_f32_e32 v149, v130, v146
	v_add_f32_e32 v146, v133, v118
	v_lshlrev_b32_e32 v118, 16, v120
	v_add_f32_e32 v133, v150, v118
	v_and_b32_e32 v118, 0xffff0000, v120
	v_add_f32_e32 v132, v151, v118
	v_lshlrev_b32_e32 v118, 16, v121
	v_add_f32_e32 v131, v152, v118
	v_and_b32_e32 v118, 0xffff0000, v121
	v_add_f32_e32 v130, v153, v118
	ds_read_b128 v[118:121], v145 offset:560
	s_waitcnt lgkmcnt(0)
	v_lshlrev_b32_e32 v150, 16, v118
	v_and_b32_e32 v118, 0xffff0000, v118
	v_add_f32_e32 v118, v148, v118
	v_lshlrev_b32_e32 v148, 16, v119
	v_and_b32_e32 v119, 0xffff0000, v119
	v_add_f32_e32 v119, v146, v119
	v_lshlrev_b32_e32 v146, 16, v120
	v_and_b32_e32 v120, 0xffff0000, v120
	v_add_f32_e32 v120, v132, v120
	v_lshlrev_b32_e32 v132, 16, v121
	v_and_b32_e32 v121, 0xffff0000, v121
	v_add_f32_e32 v121, v130, v121
	v_lshlrev_b32_e32 v130, 16, v114
	v_and_b32_e32 v114, 0xffff0000, v114
	v_add_f32_e32 v114, v118, v114
	v_lshlrev_b32_e32 v118, 16, v115
	v_and_b32_e32 v115, 0xffff0000, v115
	v_add_f32_e32 v147, v147, v148
	v_add_f32_e32 v115, v119, v115
	v_lshlrev_b32_e32 v119, 16, v116
	v_and_b32_e32 v116, 0xffff0000, v116
	v_add_f32_e32 v133, v133, v146
	v_add_f32_e32 v118, v147, v118
	v_add_f32_e32 v116, v120, v116
	v_lshlrev_b32_e32 v120, 16, v117
	v_and_b32_e32 v117, 0xffff0000, v117
	v_add_f32_e32 v149, v149, v150
	v_add_f32_e32 v131, v131, v132
	v_add_f32_e32 v119, v133, v119
	v_add_f32_e32 v117, v121, v117
	v_fma_f32 v118, v135, v118, -v124
	v_fma_f32 v115, v135, v115, -v125
	v_add_f32_e32 v130, v149, v130
	v_add_f32_e32 v120, v131, v120
	v_fma_f32 v114, v135, v114, -v123
	v_cvt_pk_bf16_f32 v115, v118, v115
	v_fma_f32 v118, v135, v119, -v126
	v_fma_f32 v116, v135, v116, -v127
	v_fma_f32 v117, v135, v117, -v129
	v_fma_f32 v121, v135, v130, -v122
	v_cvt_pk_bf16_f32 v114, v121, v114
	v_cvt_pk_bf16_f32 v116, v118, v116
	v_fma_f32 v118, v135, v120, -v128
	v_cvt_pk_bf16_f32 v117, v118, v117
	s_nop 0
	v_mfma_f32_32x32x16_bf16 v[48:63], v[98:101], v[114:117], v[48:63]
	ds_read_b128 v[98:101], v145 offset:3760
	v_mfma_f32_32x32x16_bf16 v[32:47], v[102:105], v[114:117], v[32:47]
	s_waitcnt lgkmcnt(0)
	v_lshlrev_b32_e32 v102, 16, v98
	v_and_b32_e32 v104, 0xffff0000, v98
	v_add_f32_e32 v105, 0, v104
	v_add_f32_e32 v103, 0, v102
	v_mfma_f32_32x32x16_bf16 v[16:31], v[106:109], v[114:117], v[16:31]
	v_lshlrev_b32_e32 v106, 16, v99
	v_and_b32_e32 v108, 0xffff0000, v99
	v_add_f32_e32 v107, 0, v106
	v_add_f32_e32 v109, 0, v108
	s_waitcnt vmcnt(8)
	v_mfma_f32_32x32x16_bf16 v[0:15], v[110:113], v[114:117], v[0:15]
	v_lshlrev_b32_e32 v110, 16, v100
	v_and_b32_e32 v112, 0xffff0000, v100
	v_lshlrev_b32_e32 v114, 16, v101
	v_and_b32_e32 v116, 0xffff0000, v101
	ds_read_b128 v[98:101], v145 offset:3232
	v_add_f32_e32 v111, 0, v110
	v_add_f32_e32 v113, 0, v112
	v_add_f32_e32 v115, 0, v114
	v_add_f32_e32 v117, 0, v116
	s_waitcnt lgkmcnt(0)
	v_lshlrev_b32_e32 v118, 16, v98
	v_and_b32_e32 v98, 0xffff0000, v98
	v_add_f32_e32 v105, v105, v98
	v_lshlrev_b32_e32 v98, 16, v99
	v_add_f32_e32 v107, v107, v98
	v_and_b32_e32 v98, 0xffff0000, v99
	v_add_f32_e32 v109, v109, v98
	v_lshlrev_b32_e32 v98, 16, v100
	v_add_f32_e32 v111, v111, v98
	v_and_b32_e32 v98, 0xffff0000, v100
	v_add_f32_e32 v113, v113, v98
	v_lshlrev_b32_e32 v98, 16, v101
	v_add_f32_e32 v115, v115, v98
	v_and_b32_e32 v98, 0xffff0000, v101
	v_add_f32_e32 v117, v117, v98
	ds_read_b128 v[98:101], v145 offset:2704
	v_add_f32_e32 v103, v103, v118
	s_waitcnt lgkmcnt(0)
	v_lshlrev_b32_e32 v118, 16, v98
	v_and_b32_e32 v98, 0xffff0000, v98
	v_add_f32_e32 v105, v105, v98
	v_lshlrev_b32_e32 v98, 16, v99
	v_add_f32_e32 v107, v107, v98
	v_and_b32_e32 v98, 0xffff0000, v99
	v_add_f32_e32 v109, v109, v98
	v_lshlrev_b32_e32 v98, 16, v100
	v_add_f32_e32 v111, v111, v98
	v_and_b32_e32 v98, 0xffff0000, v100
	v_add_f32_e32 v113, v113, v98
	v_lshlrev_b32_e32 v98, 16, v101
	v_add_f32_e32 v115, v115, v98
	v_and_b32_e32 v98, 0xffff0000, v101
	v_add_f32_e32 v117, v117, v98
	ds_read_b128 v[98:101], v145 offset:2176
	v_add_f32_e32 v103, v103, v118
	s_waitcnt lgkmcnt(0)
; __device__ __forceinline__ float bflo(unsigned u) { return __uint_as_float(u << 16); }
; __device__ __forceinline__ float bfhi(unsigned u) { return __uint_as_float(u & 0xffff0000u); }
; template <int W>
; __device__ __forceinline__ void pool_compute(const Params& p, int layer, int g, int dh, int tt, const int tidx) {
;     ...
;     for (int k4 = 0; k4 < 4; ++k4) {
;       const int ks = kb * 4 + k4;
;       float sum[8];
; #pragma unroll
;       for (int j = 0; j < 8; ++j) sum[j] = 0.f;
;       u32x4 x0 = *reinterpret_cast<const u32x4*>(xl + ks * 32);
; #pragma unroll
;       for (int i = 0; i < W; ++i) {
;         u32x4 xv = *reinterpret_cast<const u32x4*>(xl + ks * 32 - i * PXS);
;         sum[0] += bflo(xv.x); sum[1] += bfhi(xv.x); sum[2] += bflo(xv.y); sum[3] += bfhi(xv.y);
;         sum[4] += bflo(xv.z); sum[5] += bfhi(xv.z); sum[6] += bflo(xv.w); sum[7] += bfhi(xv.w);
;       }
;       u32x4 bfr;
;       bfr.x = pack2(sum[0] * inv - bflo(x0.x), sum[1] * inv - bfhi(x0.x));
;       bfr.y = pack2(sum[2] * inv - bflo(x0.y), sum[3] * inv - bfhi(x0.y));
;       bfr.z = pack2(sum[4] * inv - bflo(x0.z), sum[5] * inv - bfhi(x0.z));
;       bfr.w = pack2(sum[6] * inv - bflo(x0.w), sum[7] * inv - bfhi(x0.w));
; #pragma unroll
;       for (int d = 0; d < 4; ++d) acc[d] = __builtin_amdgcn_mfma_f32_32x32x16_bf16(as_bf16x8(av[k4][d]), as_bf16x8(bfr), acc[d], 0, 0, 0);
;     }
	v_lshlrev_b32_e32 v118, 16, v98
	v_and_b32_e32 v98, 0xffff0000, v98
	v_add_f32_e32 v105, v105, v98
	v_lshlrev_b32_e32 v98, 16, v99
	v_add_f32_e32 v107, v107, v98
	v_and_b32_e32 v98, 0xffff0000, v99
	v_add_f32_e32 v109, v109, v98
	v_lshlrev_b32_e32 v98, 16, v100
	v_add_f32_e32 v111, v111, v98
	v_and_b32_e32 v98, 0xffff0000, v100
	v_add_f32_e32 v113, v113, v98
	v_lshlrev_b32_e32 v98, 16, v101
	v_add_f32_e32 v115, v115, v98
	v_and_b32_e32 v98, 0xffff0000, v101
	v_add_f32_e32 v117, v117, v98
	ds_read_b128 v[98:101], v145 offset:1648
	v_add_f32_e32 v103, v103, v118
	s_waitcnt lgkmcnt(0)
	v_lshlrev_b32_e32 v118, 16, v98
	v_and_b32_e32 v98, 0xffff0000, v98
	v_add_f32_e32 v105, v105, v98
	v_lshlrev_b32_e32 v98, 16, v99
	v_add_f32_e32 v107, v107, v98
	v_and_b32_e32 v98, 0xffff0000, v99
	v_add_f32_e32 v109, v109, v98
	v_lshlrev_b32_e32 v98, 16, v100
	v_add_f32_e32 v111, v111, v98
	v_and_b32_e32 v98, 0xffff0000, v100
	v_add_f32_e32 v113, v113, v98
	v_lshlrev_b32_e32 v98, 16, v101
	v_add_f32_e32 v115, v115, v98
	v_and_b32_e32 v98, 0xffff0000, v101
	v_add_f32_e32 v117, v117, v98
	ds_read_b128 v[98:101], v145 offset:1120
	v_add_f32_e32 v103, v103, v118
	s_waitcnt lgkmcnt(0)
	v_lshlrev_b32_e32 v118, 16, v98
	v_and_b32_e32 v98, 0xffff0000, v98
	v_add_f32_e32 v105, v105, v98
	v_lshlrev_b32_e32 v98, 16, v99
	v_add_f32_e32 v107, v107, v98
	v_and_b32_e32 v98, 0xffff0000, v99
	v_add_f32_e32 v109, v109, v98
	v_lshlrev_b32_e32 v98, 16, v100
	v_add_f32_e32 v111, v111, v98
	v_and_b32_e32 v98, 0xffff0000, v100
	v_add_f32_e32 v113, v113, v98
	v_lshlrev_b32_e32 v98, 16, v101
	v_add_f32_e32 v115, v115, v98
	v_and_b32_e32 v98, 0xffff0000, v101
	v_add_f32_e32 v117, v117, v98
	ds_read_b128 v[98:101], v145 offset:592
	v_add_f32_e32 v103, v103, v118
	s_waitcnt lgkmcnt(0)
	v_lshlrev_b32_e32 v118, 16, v98
	v_and_b32_e32 v98, 0xffff0000, v98
	v_add_f32_e32 v105, v105, v98
	v_lshlrev_b32_e32 v98, 16, v99
	v_add_f32_e32 v107, v107, v98
	v_and_b32_e32 v98, 0xffff0000, v99
	v_add_f32_e32 v109, v109, v98
	v_lshlrev_b32_e32 v98, 16, v100
	v_add_f32_e32 v111, v111, v98
	v_and_b32_e32 v98, 0xffff0000, v100
	v_add_f32_e32 v113, v113, v98
	v_lshlrev_b32_e32 v98, 16, v101
	v_add_f32_e32 v115, v115, v98
	v_and_b32_e32 v98, 0xffff0000, v101
	v_add_f32_e32 v117, v117, v98
	ds_read_b128 v[98:101], v145 offset:64
	v_add_f32_e32 v103, v103, v118
	s_waitcnt lgkmcnt(0)
	v_lshlrev_b32_e32 v118, 16, v98
	v_and_b32_e32 v98, 0xffff0000, v98
	v_add_f32_e32 v103, v103, v118
	v_add_f32_e32 v98, v105, v98
	v_lshlrev_b32_e32 v105, 16, v99
	v_and_b32_e32 v99, 0xffff0000, v99
	v_add_f32_e32 v105, v107, v105
	v_add_f32_e32 v99, v109, v99
	v_lshlrev_b32_e32 v107, 16, v100
	v_and_b32_e32 v100, 0xffff0000, v100
	v_lshlrev_b32_e32 v109, 16, v101
	v_and_b32_e32 v101, 0xffff0000, v101
	v_fma_f32 v102, v135, v103, -v102
	v_fma_f32 v98, v135, v98, -v104
	v_add_f32_e32 v107, v111, v107
	v_add_f32_e32 v100, v113, v100
	v_add_f32_e32 v101, v117, v101
	v_cvt_pk_bf16_f32 v98, v102, v98
	v_fma_f32 v102, v135, v105, -v106
	v_fma_f32 v99, v135, v99, -v108
	v_add_f32_e32 v109, v115, v109
	v_cvt_pk_bf16_f32 v99, v102, v99
	v_fma_f32 v102, v135, v107, -v110
	v_fma_f32 v100, v135, v100, -v112
	v_fma_f32 v101, v135, v101, -v116
	v_cvt_pk_bf16_f32 v100, v102, v100
	v_fma_f32 v102, v135, v109, -v114
	v_cvt_pk_bf16_f32 v101, v102, v101
	s_waitcnt vmcnt(3)
	v_mfma_f32_32x32x16_bf16 v[16:31], v[88:91], v[98:101], v[16:31]
	ds_read_b128 v[88:91], v145 offset:3792
	v_mfma_f32_32x32x16_bf16 v[48:63], v[80:83], v[98:101], v[48:63]
	s_waitcnt lgkmcnt(0)
	v_lshlrev_b32_e32 v83, 16, v90
	v_and_b32_e32 v82, 0xffff0000, v90
	v_lshlrev_b32_e32 v80, 16, v91
	v_and_b32_e32 v81, 0xffff0000, v91
	v_mfma_f32_32x32x16_bf16 v[32:47], v[84:87], v[98:101], v[32:47]
	v_lshlrev_b32_e32 v86, 16, v88
	v_and_b32_e32 v87, 0xffff0000, v88
	v_lshlrev_b32_e32 v84, 16, v89
	v_and_b32_e32 v85, 0xffff0000, v89
	ds_read_b128 v[88:91], v145 offset:3264
	s_waitcnt lgkmcnt(0)
	v_lshlrev_b32_e32 v102, 16, v88
	s_waitcnt vmcnt(1)
	v_mfma_f32_32x32x16_bf16 v[0:15], v[92:95], v[98:101], v[0:15]
	v_add_f32_e32 v93, 0, v87
	v_and_b32_e32 v88, 0xffff0000, v88
	v_add_f32_e32 v94, 0, v84
	v_add_f32_e32 v93, v93, v88
	v_lshlrev_b32_e32 v88, 16, v89
	v_add_f32_e32 v95, 0, v85
	v_add_f32_e32 v94, v94, v88
	v_and_b32_e32 v88, 0xffff0000, v89
	v_add_f32_e32 v98, 0, v83
	v_add_f32_e32 v95, v95, v88
	v_lshlrev_b32_e32 v88, 16, v90
	v_add_f32_e32 v99, 0, v82
	v_add_f32_e32 v98, v98, v88
	v_and_b32_e32 v88, 0xffff0000, v90
	v_add_f32_e32 v100, 0, v80
	v_add_f32_e32 v99, v99, v88
	v_lshlrev_b32_e32 v88, 16, v91
	v_add_f32_e32 v101, 0, v81
	v_add_f32_e32 v100, v100, v88
	v_and_b32_e32 v88, 0xffff0000, v91
	v_add_f32_e32 v101, v101, v88
	ds_read_b128 v[88:91], v145 offset:2736
	v_add_f32_e32 v92, 0, v86
	v_add_f32_e32 v92, v92, v102
	s_waitcnt lgkmcnt(0)
	v_lshlrev_b32_e32 v102, 16, v88
	v_and_b32_e32 v88, 0xffff0000, v88
	v_add_f32_e32 v93, v93, v88
	v_lshlrev_b32_e32 v88, 16, v89
	v_add_f32_e32 v94, v94, v88
	v_and_b32_e32 v88, 0xffff0000, v89
	v_add_f32_e32 v95, v95, v88
	v_lshlrev_b32_e32 v88, 16, v90
	v_add_f32_e32 v98, v98, v88
	v_and_b32_e32 v88, 0xffff0000, v90
	v_add_f32_e32 v99, v99, v88
	v_lshlrev_b32_e32 v88, 16, v91
	v_add_f32_e32 v100, v100, v88
	v_and_b32_e32 v88, 0xffff0000, v91
	v_add_f32_e32 v101, v101, v88
	ds_read_b128 v[88:91], v145 offset:2208
	v_add_f32_e32 v92, v92, v102
	s_waitcnt lgkmcnt(0)
; __device__ __forceinline__ float bflo(unsigned u) { return __uint_as_float(u << 16); }
; __device__ __forceinline__ float bfhi(unsigned u) { return __uint_as_float(u & 0xffff0000u); }
; template <int W>
; __device__ __forceinline__ void pool_compute(const Params& p, int layer, int g, int dh, int tt, const int tidx) {
;     ...
;     for (int k4 = 0; k4 < 4; ++k4) {
;       const int ks = kb * 4 + k4;
;       float sum[8];
; #pragma unroll
;       for (int j = 0; j < 8; ++j) sum[j] = 0.f;
;       u32x4 x0 = *reinterpret_cast<const u32x4*>(xl + ks * 32);
; #pragma unroll
;       for (int i = 0; i < W; ++i) {
;         u32x4 xv = *reinterpret_cast<const u32x4*>(xl + ks * 32 - i * PXS);
;         sum[0] += bflo(xv.x); sum[1] += bfhi(xv.x); sum[2] += bflo(xv.y); sum[3] += bfhi(xv.y);
;         sum[4] += bflo(xv.z); sum[5] += bfhi(xv.z); sum[6] += bflo(xv.w); sum[7] += bfhi(xv.w);
;       }
;       u32x4 bfr;
;       bfr.x = pack2(sum[0] * inv - bflo(x0.x), sum[1] * inv - bfhi(x0.x));
;       bfr.y = pack2(sum[2] * inv - bflo(x0.y), sum[3] * inv - bfhi(x0.y));
;       bfr.z = pack2(sum[4] * inv - bflo(x0.z), sum[5] * inv - bfhi(x0.z));
;       bfr.w = pack2(sum[6] * inv - bflo(x0.w), sum[7] * inv - bfhi(x0.w));
; #pragma unroll
;       for (int d = 0; d < 4; ++d) acc[d] = __builtin_amdgcn_mfma_f32_32x32x16_bf16(as_bf16x8(av[k4][d]), as_bf16x8(bfr), acc[d], 0, 0, 0);
;     }
;   }
	v_lshlrev_b32_e32 v102, 16, v88
	v_and_b32_e32 v88, 0xffff0000, v88
	v_add_f32_e32 v93, v93, v88
	v_lshlrev_b32_e32 v88, 16, v89
	v_add_f32_e32 v94, v94, v88
	v_and_b32_e32 v88, 0xffff0000, v89
	v_add_f32_e32 v95, v95, v88
	v_lshlrev_b32_e32 v88, 16, v90
	v_add_f32_e32 v98, v98, v88
	v_and_b32_e32 v88, 0xffff0000, v90
	v_add_f32_e32 v99, v99, v88
	v_lshlrev_b32_e32 v88, 16, v91
	v_add_f32_e32 v100, v100, v88
	v_and_b32_e32 v88, 0xffff0000, v91
	v_add_f32_e32 v101, v101, v88
	ds_read_b128 v[88:91], v145 offset:1680
	v_add_f32_e32 v92, v92, v102
	s_waitcnt lgkmcnt(0)
	v_lshlrev_b32_e32 v102, 16, v88
	v_and_b32_e32 v88, 0xffff0000, v88
	v_add_f32_e32 v93, v93, v88
	v_lshlrev_b32_e32 v88, 16, v89
	v_add_f32_e32 v94, v94, v88
	v_and_b32_e32 v88, 0xffff0000, v89
	v_add_f32_e32 v95, v95, v88
	v_lshlrev_b32_e32 v88, 16, v90
	v_add_f32_e32 v98, v98, v88
	v_and_b32_e32 v88, 0xffff0000, v90
	v_add_f32_e32 v99, v99, v88
	v_lshlrev_b32_e32 v88, 16, v91
	v_add_f32_e32 v100, v100, v88
	v_and_b32_e32 v88, 0xffff0000, v91
	v_add_f32_e32 v101, v101, v88
	ds_read_b128 v[88:91], v145 offset:1152
	v_add_f32_e32 v92, v92, v102
	s_waitcnt lgkmcnt(0)
	v_lshlrev_b32_e32 v102, 16, v88
	v_and_b32_e32 v88, 0xffff0000, v88
	v_add_f32_e32 v93, v93, v88
	v_lshlrev_b32_e32 v88, 16, v89
	v_add_f32_e32 v94, v94, v88
	v_and_b32_e32 v88, 0xffff0000, v89
	v_add_f32_e32 v95, v95, v88
	v_lshlrev_b32_e32 v88, 16, v90
	v_add_f32_e32 v98, v98, v88
	v_and_b32_e32 v88, 0xffff0000, v90
	v_add_f32_e32 v99, v99, v88
	v_lshlrev_b32_e32 v88, 16, v91
	v_add_f32_e32 v100, v100, v88
	v_and_b32_e32 v88, 0xffff0000, v91
	v_add_f32_e32 v101, v101, v88
	ds_read_b128 v[88:91], v145 offset:624
	v_add_f32_e32 v92, v92, v102
	s_waitcnt lgkmcnt(0)
	v_lshlrev_b32_e32 v102, 16, v88
	v_and_b32_e32 v88, 0xffff0000, v88
	v_add_f32_e32 v93, v93, v88
	v_lshlrev_b32_e32 v88, 16, v89
	v_add_f32_e32 v94, v94, v88
	v_and_b32_e32 v88, 0xffff0000, v89
	v_add_f32_e32 v95, v95, v88
	v_lshlrev_b32_e32 v88, 16, v90
	v_add_f32_e32 v92, v92, v102
	v_add_f32_e32 v102, v98, v88
	v_and_b32_e32 v88, 0xffff0000, v90
	v_add_f32_e32 v103, v99, v88
	v_lshlrev_b32_e32 v88, 16, v91
	v_add_f32_e32 v104, v100, v88
	v_and_b32_e32 v88, 0xffff0000, v91
	v_add_f32_e32 v88, v101, v88
	ds_read_b128 v[98:101], v145 offset:96
	v_add_u32_e32 v145, 0x80, v145
	s_waitcnt lgkmcnt(0)
	v_lshlrev_b32_e32 v89, 16, v98
	v_add_f32_e32 v89, v92, v89
	v_and_b32_e32 v90, 0xffff0000, v98
	v_lshlrev_b32_e32 v91, 16, v99
	v_and_b32_e32 v92, 0xffff0000, v99
	v_add_f32_e32 v90, v93, v90
	v_add_f32_e32 v91, v94, v91
	v_add_f32_e32 v92, v95, v92
	v_lshlrev_b32_e32 v93, 16, v100
	v_and_b32_e32 v94, 0xffff0000, v100
	v_lshlrev_b32_e32 v95, 16, v101
	v_and_b32_e32 v98, 0xffff0000, v101
	v_add_f32_e32 v93, v102, v93
	v_add_f32_e32 v94, v103, v94
	v_add_f32_e32 v95, v104, v95
	v_add_f32_e32 v98, v88, v98
	v_fma_f32 v86, v135, v89, -v86
	v_fma_f32 v87, v135, v90, -v87
	v_cvt_pk_bf16_f32 v86, v86, v87
	v_fma_f32 v84, v135, v91, -v84
	v_fma_f32 v85, v135, v92, -v85
	v_cvt_pk_bf16_f32 v87, v84, v85
	v_fma_f32 v83, v135, v93, -v83
	v_fma_f32 v82, v135, v94, -v82
	v_cvt_pk_bf16_f32 v88, v83, v82
	v_fma_f32 v80, v135, v95, -v80
	v_fma_f32 v81, v135, v98, -v81
	v_cvt_pk_bf16_f32 v89, v80, v81
	s_nop 0
	v_mfma_f32_32x32x16_bf16 v[48:63], v[64:67], v[86:89], v[48:63]
	v_mfma_f32_32x32x16_bf16 v[32:47], v[68:71], v[86:89], v[32:47]
	v_mfma_f32_32x32x16_bf16 v[16:31], v[72:75], v[86:89], v[16:31]
	s_waitcnt vmcnt(0)
	v_mfma_f32_32x32x16_bf16 v[0:15], v[76:79], v[86:89], v[0:15]
	s_cbranch_scc1 .LBB0_180
; #define SCHED __builtin_amdgcn_sched_barrier(0)
; template <int W>
; __device__ __forceinline__ void pool_compute(const Params& p, int layer, int g, int dh, int tt, const int tidx) {
;     ...
;   u16* yo = yraw + (size_t)t * DM + g * 256;
;   f32x4 scv[4][4];
; #pragma unroll
;   for (int d = 0; d < 4; ++d)
; #pragma unroll
;     for (int rg = 0; rg < 4; ++rg) scv[d][rg] = *reinterpret_cast<const f32x4*>(psc + (dh * 4 + d) * 32 + 8 * rg + 4 * half);
;   SCHED;
; #pragma unroll
;   for (int d = 0; d < 4; ++d)
; #pragma unroll
;     for (int rg = 0; rg < 4; ++rg) {
;       int dd = (dh * 4 + d) * 32 + 8 * rg + 4 * half;
;       f32x4 sc = scv[d][rg];
;       u32x2 o = {pack2(acc[d][rg * 4 + 0] * sc[0], acc[d][rg * 4 + 1] * sc[1]), pack2(acc[d][rg * 4 + 2] * sc[2], acc[d][rg * 4 + 3] * sc[3])};
;       *reinterpret_cast<u32x2*>(yo + dd) = o;
;     }
	v_lshlrev_b32_e32 v162, 13, v140
	v_mov_b32_e32 v135, v163
	v_lshl_add_u64 v[130:131], s[86:87], 0, v[162:163]
	v_lshl_add_u64 v[64:65], s[78:79], 0, v[134:135]
	v_lshlrev_b32_e32 v162, 9, v138
	v_lshl_add_u64 v[126:127], v[64:65], 0, v[162:163]
	global_load_dwordx4 v[64:67], v[126:127], off offset:2048
	global_load_dwordx4 v[68:71], v[126:127], off offset:2080
	global_load_dwordx4 v[72:75], v[126:127], off offset:2112
	global_load_dwordx4 v[76:79], v[126:127], off offset:2144
	global_load_dwordx4 v[80:83], v[126:127], off offset:2176
	global_load_dwordx4 v[84:87], v[126:127], off offset:2208
	global_load_dwordx4 v[88:91], v[126:127], off offset:2240
	global_load_dwordx4 v[92:95], v[126:127], off offset:2272
	global_load_dwordx4 v[98:101], v[126:127], off offset:2304
	global_load_dwordx4 v[102:105], v[126:127], off offset:2336
	global_load_dwordx4 v[106:109], v[126:127], off offset:2368
	global_load_dwordx4 v[110:113], v[126:127], off offset:2400
	global_load_dwordx4 v[114:117], v[126:127], off offset:2432
	global_load_dwordx4 v[118:121], v[126:127], off offset:2464
	global_load_dwordx4 v[122:125], v[126:127], off offset:2496
	s_nop 0
	global_load_dwordx4 v[126:129], v[126:127], off offset:2528
	s_waitcnt vmcnt(15)
	v_mul_f32_e32 v48, v48, v64
	v_mul_f32_e32 v49, v49, v65
	v_cvt_pk_bf16_f32 v64, v48, v49
	v_mul_f32_e32 v48, v50, v66
	v_mul_f32_e32 v49, v51, v67
	v_cvt_pk_bf16_f32 v65, v48, v49
	v_lshlrev_b32_e32 v48, 3, v139
	v_lshl_or_b32 v162, v138, 8, v48
	v_lshl_add_u64 v[50:51], v[130:131], 0, v[162:163]
	s_mov_b64 s[14:15], 0x22900400
	v_lshl_add_u64 v[48:49], v[50:51], 0, s[14:15]
	s_mov_b32 s14, 0x22900000
	s_waitcnt vmcnt(11)
	v_mul_f32_e32 v32, v32, v80
	v_mul_f32_e32 v33, v33, v81
	s_waitcnt vmcnt(7)
	v_mul_f32_e32 v16, v16, v98
	v_mul_f32_e32 v17, v17, v99
	s_waitcnt vmcnt(3)
	v_mul_f32_e32 v0, v0, v114
	v_mul_f32_e32 v1, v1, v115
	v_add_co_u32_e32 v50, vcc, s14, v50
	v_cvt_pk_bf16_f32 v32, v32, v33
	v_mul_f32_e32 v33, v34, v82
	v_cvt_pk_bf16_f32 v16, v16, v17
	v_mul_f32_e32 v17, v18, v100
	v_cvt_pk_bf16_f32 v0, v0, v1
	v_mul_f32_e32 v1, v2, v116
	v_addc_co_u32_e32 v51, vcc, 0, v51, vcc
	v_mul_f32_e32 v34, v35, v83
	v_cvt_pk_bf16_f32 v33, v33, v34
	v_mul_f32_e32 v18, v19, v101
	v_cvt_pk_bf16_f32 v17, v17, v18
	v_mul_f32_e32 v2, v3, v117
	v_cvt_pk_bf16_f32 v1, v1, v2
	global_store_dwordx2 v[50:51], v[64:65], off offset:1024
	v_mul_f32_e32 v50, v52, v68
	v_mul_f32_e32 v51, v53, v69
	global_store_dwordx2 v[48:49], v[32:33], off offset:64
	v_mul_f32_e32 v32, v36, v84
	v_mul_f32_e32 v33, v37, v85
	global_store_dwordx2 v[48:49], v[16:17], off offset:128
	v_mul_f32_e32 v16, v20, v102
	v_mul_f32_e32 v17, v21, v103
	global_store_dwordx2 v[48:49], v[0:1], off offset:192
	s_waitcnt vmcnt(6)
	v_mul_f32_e32 v0, v4, v118
	v_mul_f32_e32 v1, v5, v119
	v_cvt_pk_bf16_f32 v50, v50, v51
	v_mul_f32_e32 v51, v54, v70
	v_cvt_pk_bf16_f32 v32, v32, v33
	v_mul_f32_e32 v33, v38, v86
	v_cvt_pk_bf16_f32 v16, v16, v17
	v_mul_f32_e32 v17, v22, v104
	v_cvt_pk_bf16_f32 v0, v0, v1
	v_mul_f32_e32 v1, v6, v120
	v_mul_f32_e32 v52, v55, v71
	v_cvt_pk_bf16_f32 v51, v51, v52
	v_mul_f32_e32 v34, v39, v87
	v_cvt_pk_bf16_f32 v33, v33, v34
	v_mul_f32_e32 v18, v23, v105
	v_cvt_pk_bf16_f32 v17, v17, v18
	v_mul_f32_e32 v2, v7, v121
	v_cvt_pk_bf16_f32 v1, v1, v2
	global_store_dwordx2 v[48:49], v[50:51], off offset:16
	v_mul_f32_e32 v50, v56, v72
	v_mul_f32_e32 v51, v57, v73
	global_store_dwordx2 v[48:49], v[32:33], off offset:80
	v_mul_f32_e32 v32, v40, v88
	v_mul_f32_e32 v33, v41, v89
	global_store_dwordx2 v[48:49], v[16:17], off offset:144
	v_mul_f32_e32 v16, v24, v106
	v_mul_f32_e32 v17, v25, v107
	global_store_dwordx2 v[48:49], v[0:1], off offset:208
	s_waitcnt vmcnt(9)
	v_mul_f32_e32 v0, v8, v122
	v_mul_f32_e32 v1, v9, v123
	v_cvt_pk_bf16_f32 v50, v50, v51
	v_mul_f32_e32 v51, v58, v74
	v_cvt_pk_bf16_f32 v32, v32, v33
	v_mul_f32_e32 v33, v42, v90
	v_cvt_pk_bf16_f32 v16, v16, v17
	v_mul_f32_e32 v17, v26, v108
	v_cvt_pk_bf16_f32 v0, v0, v1
	v_mul_f32_e32 v1, v10, v124
	v_mul_f32_e32 v52, v59, v75
	v_cvt_pk_bf16_f32 v51, v51, v52
	v_mul_f32_e32 v34, v43, v91
	v_cvt_pk_bf16_f32 v33, v33, v34
	v_mul_f32_e32 v18, v27, v109
	v_cvt_pk_bf16_f32 v17, v17, v18
	v_mul_f32_e32 v2, v11, v125
	v_cvt_pk_bf16_f32 v1, v1, v2
	global_store_dwordx2 v[48:49], v[50:51], off offset:32
	v_mul_f32_e32 v50, v60, v76
	v_mul_f32_e32 v51, v61, v77
	global_store_dwordx2 v[48:49], v[32:33], off offset:96
	v_mul_f32_e32 v32, v44, v92
	v_mul_f32_e32 v33, v45, v93
	global_store_dwordx2 v[48:49], v[16:17], off offset:160
	v_mul_f32_e32 v16, v28, v110
	v_mul_f32_e32 v17, v29, v111
	global_store_dwordx2 v[48:49], v[0:1], off offset:224
	s_waitcnt vmcnt(12)
	v_mul_f32_e32 v0, v12, v126
	v_mul_f32_e32 v1, v13, v127
	v_cvt_pk_bf16_f32 v50, v50, v51
	v_mul_f32_e32 v51, v62, v78
	v_cvt_pk_bf16_f32 v32, v32, v33
	v_mul_f32_e32 v33, v46, v94
	v_cvt_pk_bf16_f32 v16, v16, v17
	v_mul_f32_e32 v17, v30, v112
	v_cvt_pk_bf16_f32 v0, v0, v1
	v_mul_f32_e32 v1, v14, v128
	s_xor_b64 s[14:15], exec, -1
	v_mul_f32_e32 v52, v63, v79
	v_cvt_pk_bf16_f32 v51, v51, v52
	global_store_dwordx2 v[48:49], v[50:51], off offset:48
	v_mul_f32_e32 v34, v47, v95
	v_cvt_pk_bf16_f32 v33, v33, v34
	global_store_dwordx2 v[48:49], v[32:33], off offset:112
	v_mul_f32_e32 v18, v31, v113
	v_cvt_pk_bf16_f32 v17, v17, v18
	global_store_dwordx2 v[48:49], v[16:17], off offset:176
	v_mul_f32_e32 v2, v15, v129
	v_cvt_pk_bf16_f32 v1, v1, v2
	s_setprio 0

; __device__ __forceinline__ float bflo(unsigned u) { return __uint_as_float(u << 16); }
; __device__ __forceinline__ float bfhi(unsigned u) { return __uint_as_float(u & 0xffff0000u); }
; #define SCHED __builtin_amdgcn_sched_barrier(0)
; template <int W>
; __device__ __forceinline__ void pool_compute(const Params& p, int layer, int g, int dh, int tt, const int tidx) {
;   const int lane = tidx & 63, n = lane & 31, half = lane >> 5;
;   const int t = tt * 32 + n, pos = t & (SEQ - 1);
;   const int cnt = min(pos + 1, W);
;   const float inv = 1.f / (float)cnt;
;   const char* wpb = (const char*)(p.ws + WS_WPOOL + (size_t)layer * SZ_WPOOL) + (size_t)g * 131072;
;   u16* yraw = (u16*)(p.ws + WS_YRAW);
;   const float* psc = p.pool_scale + layer * 1024 + g * 256;
;   const char* xl = smem + g * (PROWS * PXS) + (15 + n) * PXS + half * 16;
;   const unsigned woff = (unsigned)(n * 512 + half * 16);
;   f32x16 acc[4];
; #pragma unroll
;   for (int d = 0; d < 4; ++d)
; #pragma unroll
;     for (int i = 0; i < 16; ++i) acc[d][i] = 0.f;
; #pragma unroll 1
;   for (int kb = 0; kb < 4; ++kb) {
;     u32x4 av[4][4];
; #pragma unroll
;     for (int k4 = 0; k4 < 4; ++k4)
; #pragma unroll
;       for (int d = 0; d < 4; ++d)
;         av[k4][d] = *reinterpret_cast<const u32x4*>(wpb + (woff + (unsigned)(((dh * 4 + d) * 32) * 512 + (kb * 4 + k4) * 32)));
;     SCHED;
; #pragma unroll
;     for (int k4 = 0; k4 < 4; ++k4) {
;       const int ks = kb * 4 + k4;
;       float sum[8];
; #pragma unroll
;       for (int j = 0; j < 8; ++j) sum[j] = 0.f;
;       u32x4 x0 = *reinterpret_cast<const u32x4*>(xl + ks * 32);
; #pragma unroll
;       for (int i = 0; i < W; ++i) {
;         u32x4 xv = *reinterpret_cast<const u32x4*>(xl + ks * 32 - i * PXS);
;         sum[0] += bflo(xv.x); sum[1] += bfhi(xv.x); sum[2] += bflo(xv.y); sum[3] += bfhi(xv.y);
;         sum[4] += bflo(xv.z); sum[5] += bfhi(xv.z); sum[6] += bflo(xv.w); sum[7] += bfhi(xv.w);
;       }
.LBB0_184:
	s_setprio 2
	v_min_u32_e32 v0, 15, v142
	v_add_u32_e32 v0, 1, v0
	v_cvt_f32_ubyte0_e32 v0, v0
	v_div_scale_f32 v1, s[12:13], v0, v0, 1.0
	v_rcp_f32_e32 v2, v1
	v_div_scale_f32 v3, vcc, 1.0, v0, 1.0
	v_readlane_b32 s12, v255, 37
	v_fma_f32 v4, -v1, v2, 1.0
	v_fmac_f32_e32 v2, v4, v2
	v_mul_f32_e32 v4, v3, v2
	v_fma_f32 v5, -v1, v4, v3
	v_fmac_f32_e32 v4, v5, v2
	v_fma_f32 v1, -v1, v4, v3
	v_div_fmas_f32 v1, v1, v2, v4
	v_readlane_b32 s13, v255, 38
	v_mov_b32_e32 v48, 0
	v_div_fixup_f32 v135, v1, v0, 1.0
	v_add3_u32 v143, v141, v134, 32
	v_lshl_add_u64 v[136:137], s[12:13], 0, v[162:163]
	s_mov_b32 s12, 0
	v_mov_b32_e32 v49, v48
	v_mov_b32_e32 v50, v48
	v_mov_b32_e32 v51, v48
	v_mov_b32_e32 v52, v48
	v_mov_b32_e32 v53, v48
	v_mov_b32_e32 v54, v48
	v_mov_b32_e32 v55, v48
	v_mov_b32_e32 v56, v48
	v_mov_b32_e32 v57, v48
	v_mov_b32_e32 v58, v48
	v_mov_b32_e32 v59, v48
	v_mov_b32_e32 v60, v48
	v_mov_b32_e32 v61, v48
	v_mov_b32_e32 v62, v48
	v_mov_b32_e32 v63, v48
	v_mov_b32_e32 v32, v48
	v_mov_b32_e32 v33, v48
	v_mov_b32_e32 v34, v48
	v_mov_b32_e32 v35, v48
	v_mov_b32_e32 v36, v48
	v_mov_b32_e32 v37, v48
	v_mov_b32_e32 v38, v48
	v_mov_b32_e32 v39, v48
	v_mov_b32_e32 v40, v48
	v_mov_b32_e32 v41, v48
	v_mov_b32_e32 v42, v48
	v_mov_b32_e32 v43, v48
	v_mov_b32_e32 v44, v48
	v_mov_b32_e32 v45, v48
	v_mov_b32_e32 v46, v48
	v_mov_b32_e32 v47, v48
	v_mov_b32_e32 v16, v48
	v_mov_b32_e32 v17, v48
	v_mov_b32_e32 v18, v48
	v_mov_b32_e32 v19, v48
	v_mov_b32_e32 v20, v48
	v_mov_b32_e32 v21, v48
	v_mov_b32_e32 v22, v48
	v_mov_b32_e32 v23, v48
	v_mov_b32_e32 v24, v48
	v_mov_b32_e32 v25, v48
	v_mov_b32_e32 v26, v48
	v_mov_b32_e32 v27, v48
	v_mov_b32_e32 v28, v48
	v_mov_b32_e32 v29, v48
	v_mov_b32_e32 v30, v48
	v_mov_b32_e32 v31, v48
	v_mov_b32_e32 v0, v48
	v_mov_b32_e32 v1, v48
	v_mov_b32_e32 v2, v48
	v_mov_b32_e32 v3, v48
	v_mov_b32_e32 v4, v48
	v_mov_b32_e32 v5, v48
	v_mov_b32_e32 v6, v48
	v_mov_b32_e32 v7, v48
	v_mov_b32_e32 v8, v48
	v_mov_b32_e32 v9, v48
	v_mov_b32_e32 v10, v48
	v_mov_b32_e32 v11, v48
	v_mov_b32_e32 v12, v48
	v_mov_b32_e32 v13, v48
	v_mov_b32_e32 v14, v48
	v_mov_b32_e32 v15, v48
	s_movk_i32 s13, 0x4000
	s_mov_b32 s14, 0x8000
	s_mov_b32 s15, 0xc000
	s_mov_b64 s[16:17], 0x80
.LBB0_185:
	v_add_co_u32_e32 v68, vcc, s13, v136
	s_nop 1
	v_addc_co_u32_e32 v69, vcc, 0, v137, vcc
	v_add_co_u32_e32 v72, vcc, s14, v136
	s_nop 1
	v_addc_co_u32_e32 v73, vcc, 0, v137, vcc
	v_add_co_u32_e32 v76, vcc, s15, v136
	s_nop 1
	v_addc_co_u32_e32 v77, vcc, 0, v137, vcc
	global_load_dwordx4 v[114:117], v[136:137], off
	global_load_dwordx4 v[98:101], v[136:137], off offset:32
	global_load_dwordx4 v[118:121], v[68:69], off
	global_load_dwordx4 v[102:105], v[68:69], off offset:32
	global_load_dwordx4 v[122:125], v[72:73], off
	global_load_dwordx4 v[106:109], v[72:73], off offset:32
	global_load_dwordx4 v[126:129], v[76:77], off
	global_load_dwordx4 v[110:113], v[76:77], off offset:32
	global_load_dwordx4 v[80:83], v[136:137], off offset:64
	global_load_dwordx4 v[64:67], v[136:137], off offset:96
	global_load_dwordx4 v[84:87], v[68:69], off offset:64
	s_nop 0
	global_load_dwordx4 v[68:71], v[68:69], off offset:96
	s_nop 0
	global_load_dwordx4 v[88:91], v[72:73], off offset:64
	s_nop 0
	global_load_dwordx4 v[72:75], v[72:73], off offset:96
	s_nop 0
	global_load_dwordx4 v[92:95], v[76:77], off offset:64
	s_nop 0
	global_load_dwordx4 v[76:79], v[76:77], off offset:96
	v_add_u32_e32 v144, s12, v143
	v_add_u32_e32 v131, 0x141c0, v144
	ds_read_b128 v[150:153], v131
	v_add_u32_e32 v154, 0x13fb0, v144
	ds_read_b128 v[154:157], v154
	v_add_u32_e32 v130, 0x122d0, v144
	s_addk_i32 s12, 0x80
	s_waitcnt lgkmcnt(1)
	v_and_b32_e32 v146, 0xffff0000, v150
	v_add_f32_e32 v132, 0, v146
	v_lshlrev_b32_e32 v147, 16, v151
	s_waitcnt lgkmcnt(0)
	v_lshlrev_b32_e32 v165, 16, v154
	v_and_b32_e32 v154, 0xffff0000, v154
	v_add_f32_e32 v133, 0, v147
	v_and_b32_e32 v148, 0xffff0000, v151
	v_add_f32_e32 v132, v132, v154
	v_lshlrev_b32_e32 v154, 16, v155
	v_add_f32_e32 v158, 0, v148
	v_lshlrev_b32_e32 v149, 16, v152
	v_add_f32_e32 v133, v133, v154
	v_and_b32_e32 v154, 0xffff0000, v155
	v_lshlrev_b32_e32 v145, 16, v150
	v_add_f32_e32 v159, 0, v149
	v_and_b32_e32 v150, 0xffff0000, v152
	v_add_f32_e32 v158, v158, v154
	v_lshlrev_b32_e32 v154, 16, v156
	v_add_f32_e32 v160, 0, v150
	v_lshlrev_b32_e32 v151, 16, v153
	v_add_f32_e32 v159, v159, v154
	v_and_b32_e32 v154, 0xffff0000, v156
	v_add_f32_e32 v161, 0, v151
	v_and_b32_e32 v152, 0xffff0000, v153
	v_add_f32_e32 v160, v160, v154
	v_lshlrev_b32_e32 v154, 16, v157
	v_add_f32_e32 v153, 0, v152
	v_add_f32_e32 v161, v161, v154
	v_and_b32_e32 v154, 0xffff0000, v157
	v_add_f32_e32 v153, v153, v154
	v_add_u32_e32 v154, 0x13da0, v144
	ds_read_b128 v[154:157], v154
	v_add_f32_e32 v131, 0, v145
	v_add_f32_e32 v131, v131, v165
	v_lshl_add_u64 v[136:137], v[136:137], 0, s[16:17]
	s_cmpk_lg_i32 s12, 0x200
	s_waitcnt lgkmcnt(0)
	v_add_u32_e32 v172, 0x13b90, v144
	ds_read_b128 v[172:175], v172
	v_add_u32_e32 v168, 0x13980, v144
	ds_read_b128 v[168:171], v168
	v_lshlrev_b32_e32 v165, 16, v154
	v_and_b32_e32 v154, 0xffff0000, v154
	v_add_f32_e32 v132, v132, v154
	v_lshlrev_b32_e32 v154, 16, v155
	v_add_f32_e32 v133, v133, v154
	v_and_b32_e32 v154, 0xffff0000, v155
	v_add_f32_e32 v158, v158, v154
	v_lshlrev_b32_e32 v154, 16, v156
	v_add_f32_e32 v159, v159, v154
	v_and_b32_e32 v154, 0xffff0000, v156
	v_add_f32_e32 v160, v160, v154
	v_lshlrev_b32_e32 v154, 16, v157
	v_add_f32_e32 v161, v161, v154
	v_and_b32_e32 v154, 0xffff0000, v157
	v_add_f32_e32 v153, v153, v154
	v_add_f32_e32 v131, v131, v165
	s_waitcnt lgkmcnt(1)
; __device__ __forceinline__ float bflo(unsigned u) { return __uint_as_float(u << 16); }
; __device__ __forceinline__ float bfhi(unsigned u) { return __uint_as_float(u & 0xffff0000u); }
; template <int W>
; __device__ __forceinline__ void pool_compute(const Params& p, int layer, int g, int dh, int tt, const int tidx) {
;     ...
;       u32x4 x0 = *reinterpret_cast<const u32x4*>(xl + ks * 32);
; #pragma unroll
;       for (int i = 0; i < W; ++i) {
;         u32x4 xv = *reinterpret_cast<const u32x4*>(xl + ks * 32 - i * PXS);
;         sum[0] += bflo(xv.x); sum[1] += bfhi(xv.x); sum[2] += bflo(xv.y); sum[3] += bfhi(xv.y);
;         sum[4] += bflo(xv.z); sum[5] += bfhi(xv.z); sum[6] += bflo(xv.w); sum[7] += bfhi(xv.w);
;       }
	v_add_u32_e32 v154, 0x13770, v144
	ds_read_b128 v[154:157], v154
	v_lshlrev_b32_e32 v165, 16, v172
	v_and_b32_e32 v172, 0xffff0000, v172
	v_add_f32_e32 v132, v132, v172
	v_lshlrev_b32_e32 v172, 16, v173
	v_add_f32_e32 v133, v133, v172
	v_and_b32_e32 v172, 0xffff0000, v173
	v_add_f32_e32 v158, v158, v172
	v_lshlrev_b32_e32 v172, 16, v174
	v_add_f32_e32 v159, v159, v172
	v_and_b32_e32 v172, 0xffff0000, v174
	v_add_f32_e32 v160, v160, v172
	v_lshlrev_b32_e32 v172, 16, v175
	v_add_f32_e32 v161, v161, v172
	v_and_b32_e32 v172, 0xffff0000, v175
	v_add_f32_e32 v153, v153, v172
	v_add_f32_e32 v131, v131, v165
	s_waitcnt lgkmcnt(1)
	v_add_u32_e32 v172, 0x13560, v144
	ds_read_b128 v[172:175], v172
	v_lshlrev_b32_e32 v165, 16, v168
	v_and_b32_e32 v168, 0xffff0000, v168
	v_add_f32_e32 v132, v132, v168
	v_lshlrev_b32_e32 v168, 16, v169
	v_add_f32_e32 v133, v133, v168
	v_and_b32_e32 v168, 0xffff0000, v169
	v_add_f32_e32 v158, v158, v168
	v_lshlrev_b32_e32 v168, 16, v170
	v_add_f32_e32 v159, v159, v168
	v_and_b32_e32 v168, 0xffff0000, v170
	v_add_f32_e32 v160, v160, v168
	v_lshlrev_b32_e32 v168, 16, v171
	v_add_f32_e32 v161, v161, v168
	v_and_b32_e32 v168, 0xffff0000, v171
	v_add_f32_e32 v153, v153, v168
	v_add_f32_e32 v131, v131, v165
	s_waitcnt lgkmcnt(1)
	v_add_u32_e32 v168, 0x13350, v144
	ds_read_b128 v[168:171], v168
	v_lshlrev_b32_e32 v165, 16, v154
	v_and_b32_e32 v154, 0xffff0000, v154
	v_add_f32_e32 v132, v132, v154
	v_lshlrev_b32_e32 v154, 16, v155
	v_add_f32_e32 v133, v133, v154
	v_and_b32_e32 v154, 0xffff0000, v155
	v_add_f32_e32 v158, v158, v154
	v_lshlrev_b32_e32 v154, 16, v156
	v_add_f32_e32 v159, v159, v154
	v_and_b32_e32 v154, 0xffff0000, v156
	v_add_f32_e32 v160, v160, v154
	v_lshlrev_b32_e32 v154, 16, v157
	v_add_f32_e32 v161, v161, v154
	v_and_b32_e32 v154, 0xffff0000, v157
	v_add_f32_e32 v153, v153, v154
	v_add_f32_e32 v131, v131, v165
	s_waitcnt lgkmcnt(1)
	v_add_u32_e32 v154, 0x13140, v144
	ds_read_b128 v[154:157], v154
	v_lshlrev_b32_e32 v165, 16, v172
	v_and_b32_e32 v172, 0xffff0000, v172
	v_add_f32_e32 v132, v132, v172
	v_lshlrev_b32_e32 v172, 16, v173
	v_add_f32_e32 v133, v133, v172
	v_and_b32_e32 v172, 0xffff0000, v173
	v_add_f32_e32 v158, v158, v172
	v_lshlrev_b32_e32 v172, 16, v174
	v_add_f32_e32 v159, v159, v172
	v_and_b32_e32 v172, 0xffff0000, v174
	v_add_f32_e32 v160, v160, v172
	v_lshlrev_b32_e32 v172, 16, v175
	v_add_f32_e32 v161, v161, v172
	v_and_b32_e32 v172, 0xffff0000, v175
	v_add_f32_e32 v153, v153, v172
	v_add_f32_e32 v131, v131, v165
	s_waitcnt lgkmcnt(1)
	v_add_u32_e32 v172, 0x12f30, v144
	ds_read_b128 v[172:175], v172
	v_lshlrev_b32_e32 v165, 16, v168
	v_and_b32_e32 v168, 0xffff0000, v168
	v_add_f32_e32 v132, v132, v168
	v_lshlrev_b32_e32 v168, 16, v169
	v_add_f32_e32 v133, v133, v168
	v_and_b32_e32 v168, 0xffff0000, v169
	v_add_f32_e32 v158, v158, v168
	v_lshlrev_b32_e32 v168, 16, v170
	v_add_f32_e32 v159, v159, v168
	v_and_b32_e32 v168, 0xffff0000, v170
	v_add_f32_e32 v160, v160, v168
	v_lshlrev_b32_e32 v168, 16, v171
	v_add_f32_e32 v161, v161, v168
	v_and_b32_e32 v168, 0xffff0000, v171
	v_add_f32_e32 v153, v153, v168
	v_add_f32_e32 v131, v131, v165
	s_waitcnt lgkmcnt(1)
	v_add_u32_e32 v168, 0x12d20, v144
	ds_read_b128 v[168:171], v168
	v_lshlrev_b32_e32 v165, 16, v154
	v_and_b32_e32 v154, 0xffff0000, v154
	v_add_f32_e32 v132, v132, v154
	v_lshlrev_b32_e32 v154, 16, v155
	v_add_f32_e32 v133, v133, v154
	v_and_b32_e32 v154, 0xffff0000, v155
	v_add_f32_e32 v158, v158, v154
	v_lshlrev_b32_e32 v154, 16, v156
	v_add_f32_e32 v159, v159, v154
	v_and_b32_e32 v154, 0xffff0000, v156
	v_add_f32_e32 v160, v160, v154
	v_lshlrev_b32_e32 v154, 16, v157
	v_add_f32_e32 v161, v161, v154
	v_and_b32_e32 v154, 0xffff0000, v157
	v_add_f32_e32 v153, v153, v154
	v_add_f32_e32 v131, v131, v165
	s_waitcnt lgkmcnt(1)
	v_add_u32_e32 v154, 0x12b10, v144
	ds_read_b128 v[154:157], v154
	v_lshlrev_b32_e32 v165, 16, v172
	v_and_b32_e32 v172, 0xffff0000, v172
	v_add_f32_e32 v132, v132, v172
	v_lshlrev_b32_e32 v172, 16, v173
	v_add_f32_e32 v133, v133, v172
	v_and_b32_e32 v172, 0xffff0000, v173
	v_add_f32_e32 v158, v158, v172
	v_lshlrev_b32_e32 v172, 16, v174
	v_add_f32_e32 v159, v159, v172
	v_and_b32_e32 v172, 0xffff0000, v174
	v_add_f32_e32 v160, v160, v172
	v_lshlrev_b32_e32 v172, 16, v175
	v_add_f32_e32 v161, v161, v172
	v_and_b32_e32 v172, 0xffff0000, v175
	v_add_f32_e32 v153, v153, v172
	v_add_f32_e32 v131, v131, v165
	s_waitcnt lgkmcnt(1)
	v_add_u32_e32 v172, 0x12900, v144
	ds_read_b128 v[172:175], v172
	v_lshlrev_b32_e32 v165, 16, v168
	v_and_b32_e32 v168, 0xffff0000, v168
	v_add_f32_e32 v132, v132, v168
	v_lshlrev_b32_e32 v168, 16, v169
	v_add_f32_e32 v133, v133, v168
	v_and_b32_e32 v168, 0xffff0000, v169
	v_add_f32_e32 v158, v158, v168
	v_lshlrev_b32_e32 v168, 16, v170
	v_add_f32_e32 v159, v159, v168
	v_and_b32_e32 v168, 0xffff0000, v170
	v_add_f32_e32 v160, v160, v168
	v_lshlrev_b32_e32 v168, 16, v171
	v_add_f32_e32 v161, v161, v168
	v_and_b32_e32 v168, 0xffff0000, v171
	v_add_f32_e32 v153, v153, v168
	v_add_f32_e32 v131, v131, v165
	s_waitcnt lgkmcnt(1)
	v_add_u32_e32 v168, 0x126f0, v144
	ds_read_b128 v[168:171], v168
	v_lshlrev_b32_e32 v165, 16, v154
	v_and_b32_e32 v154, 0xffff0000, v154
	v_add_f32_e32 v132, v132, v154
	v_lshlrev_b32_e32 v154, 16, v155
	v_add_f32_e32 v133, v133, v154
	v_and_b32_e32 v154, 0xffff0000, v155
	v_add_f32_e32 v158, v158, v154
	v_lshlrev_b32_e32 v154, 16, v156
	v_add_f32_e32 v159, v159, v154
	v_and_b32_e32 v154, 0xffff0000, v156
	v_add_f32_e32 v160, v160, v154
	v_lshlrev_b32_e32 v154, 16, v157
	v_add_f32_e32 v161, v161, v154
	v_and_b32_e32 v154, 0xffff0000, v157
	v_add_f32_e32 v153, v153, v154
	v_add_f32_e32 v131, v131, v165
	s_waitcnt lgkmcnt(1)
; __device__ __forceinline__ float bflo(unsigned u) { return __uint_as_float(u << 16); }
; __device__ __forceinline__ float bfhi(unsigned u) { return __uint_as_float(u & 0xffff0000u); }
; template <int W>
; __device__ __forceinline__ void pool_compute(const Params& p, int layer, int g, int dh, int tt, const int tidx) {
;     ...
;       u32x4 x0 = *reinterpret_cast<const u32x4*>(xl + ks * 32);
; #pragma unroll
;       for (int i = 0; i < W; ++i) {
;         u32x4 xv = *reinterpret_cast<const u32x4*>(xl + ks * 32 - i * PXS);
;         sum[0] += bflo(xv.x); sum[1] += bfhi(xv.x); sum[2] += bflo(xv.y); sum[3] += bfhi(xv.y);
;         sum[4] += bflo(xv.z); sum[5] += bfhi(xv.z); sum[6] += bflo(xv.w); sum[7] += bfhi(xv.w);
;       }
;       u32x4 bfr;
;       bfr.x = pack2(sum[0] * inv - bflo(x0.x), sum[1] * inv - bfhi(x0.x));
;       bfr.y = pack2(sum[2] * inv - bflo(x0.y), sum[3] * inv - bfhi(x0.y));
;       bfr.z = pack2(sum[4] * inv - bflo(x0.z), sum[5] * inv - bfhi(x0.z));
;       bfr.w = pack2(sum[6] * inv - bflo(x0.w), sum[7] * inv - bfhi(x0.w));
; #pragma unroll
;       for (int d = 0; d < 4; ++d) acc[d] = __builtin_amdgcn_mfma_f32_32x32x16_bf16(as_bf16x8(av[k4][d]), as_bf16x8(bfr), acc[d], 0, 0, 0);
;     }
	v_add_u32_e32 v154, 0x124e0, v144
	ds_read_b128 v[154:157], v154
	v_lshlrev_b32_e32 v165, 16, v172
	v_and_b32_e32 v172, 0xffff0000, v172
	v_add_f32_e32 v132, v132, v172
	v_lshlrev_b32_e32 v172, 16, v173
	v_add_f32_e32 v133, v133, v172
	v_and_b32_e32 v172, 0xffff0000, v173
	v_add_f32_e32 v158, v158, v172
	v_lshlrev_b32_e32 v172, 16, v174
	v_add_f32_e32 v159, v159, v172
	v_and_b32_e32 v172, 0xffff0000, v174
	v_add_f32_e32 v160, v160, v172
	v_lshlrev_b32_e32 v172, 16, v175
	v_add_f32_e32 v161, v161, v172
	v_and_b32_e32 v172, 0xffff0000, v175
	v_add_f32_e32 v153, v153, v172
	v_add_f32_e32 v131, v131, v165
	s_waitcnt lgkmcnt(1)
	v_lshlrev_b32_e32 v165, 16, v168
	v_and_b32_e32 v168, 0xffff0000, v168
	v_add_f32_e32 v132, v132, v168
	v_lshlrev_b32_e32 v168, 16, v169
	v_add_f32_e32 v133, v133, v168
	v_and_b32_e32 v168, 0xffff0000, v169
	v_add_f32_e32 v158, v158, v168
	v_lshlrev_b32_e32 v168, 16, v170
	v_add_f32_e32 v159, v159, v168
	v_and_b32_e32 v168, 0xffff0000, v170
	v_add_f32_e32 v160, v160, v168
	v_lshlrev_b32_e32 v168, 16, v171
	v_add_f32_e32 v161, v161, v168
	v_and_b32_e32 v168, 0xffff0000, v171
	v_add_f32_e32 v153, v153, v168
	v_add_f32_e32 v131, v131, v165
	s_waitcnt lgkmcnt(0)
	v_lshlrev_b32_e32 v165, 16, v154
	v_add_f32_e32 v165, v131, v165
	v_and_b32_e32 v131, 0xffff0000, v154
	v_add_f32_e32 v154, v132, v131
	v_lshlrev_b32_e32 v131, 16, v155
	v_add_f32_e32 v166, v133, v131
	v_and_b32_e32 v131, 0xffff0000, v155
	v_add_f32_e32 v155, v158, v131
	v_lshlrev_b32_e32 v131, 16, v156
	v_add_f32_e32 v158, v159, v131
	v_and_b32_e32 v131, 0xffff0000, v156
	v_add_f32_e32 v156, v160, v131
	v_lshlrev_b32_e32 v131, 16, v157
	v_add_f32_e32 v159, v161, v131
	v_and_b32_e32 v131, 0xffff0000, v157
	v_add_f32_e32 v153, v153, v131
	ds_read_b128 v[130:133], v130
	s_waitcnt lgkmcnt(0)
	v_lshlrev_b32_e32 v157, 16, v130
	v_and_b32_e32 v130, 0xffff0000, v130
	v_add_f32_e32 v130, v154, v130
	v_lshlrev_b32_e32 v154, 16, v131
	v_and_b32_e32 v131, 0xffff0000, v131
	v_add_f32_e32 v157, v165, v157
	v_add_f32_e32 v131, v155, v131
	v_lshlrev_b32_e32 v155, 16, v132
	v_and_b32_e32 v132, 0xffff0000, v132
	v_add_f32_e32 v154, v166, v154
	v_add_f32_e32 v132, v156, v132
	v_lshlrev_b32_e32 v156, 16, v133
	v_and_b32_e32 v133, 0xffff0000, v133
	v_fma_f32 v145, v135, v157, -v145
	v_fma_f32 v130, v135, v130, -v146
	v_add_f32_e32 v155, v158, v155
	v_add_f32_e32 v133, v153, v133
	v_cvt_pk_bf16_f32 v130, v145, v130
	v_fma_f32 v145, v135, v154, -v147
	v_fma_f32 v131, v135, v131, -v148
	v_add_f32_e32 v156, v159, v156
	v_cvt_pk_bf16_f32 v131, v145, v131
	v_fma_f32 v145, v135, v155, -v149
	v_fma_f32 v132, v135, v132, -v150
	v_fma_f32 v133, v135, v133, -v152
	v_cvt_pk_bf16_f32 v132, v145, v132
	v_fma_f32 v145, v135, v156, -v151
	v_cvt_pk_bf16_f32 v133, v145, v133
	s_waitcnt vmcnt(15)
	v_mfma_f32_32x32x16_bf16 v[48:63], v[114:117], v[130:133], v[48:63]
	v_add_u32_e32 v114, 0x141e0, v144
	s_waitcnt vmcnt(13)
	v_mfma_f32_32x32x16_bf16 v[32:47], v[118:121], v[130:133], v[32:47]
	ds_read_b128 v[118:121], v114
	s_waitcnt vmcnt(11)
	v_mfma_f32_32x32x16_bf16 v[16:31], v[122:125], v[130:133], v[16:31]
	v_add_u32_e32 v122, 0x13fd0, v144
	ds_read_b128 v[122:125], v122
	s_waitcnt lgkmcnt(1)
	v_and_b32_e32 v115, 0xffff0000, v118
	v_lshlrev_b32_e32 v116, 16, v119
	v_and_b32_e32 v117, 0xffff0000, v119
	v_lshlrev_b32_e32 v114, 16, v118
	s_waitcnt lgkmcnt(0)
	v_lshlrev_b32_e32 v145, 16, v122
	s_waitcnt vmcnt(9)
	v_mfma_f32_32x32x16_bf16 v[0:15], v[126:129], v[130:133], v[0:15]
	v_add_f32_e32 v127, 0, v115
	v_and_b32_e32 v122, 0xffff0000, v122
	v_add_f32_e32 v128, 0, v116
	v_add_f32_e32 v127, v127, v122
	v_lshlrev_b32_e32 v122, 16, v123
	v_add_f32_e32 v129, 0, v117
	v_lshlrev_b32_e32 v118, 16, v120
	v_add_f32_e32 v128, v128, v122
	v_and_b32_e32 v122, 0xffff0000, v123
	v_add_f32_e32 v130, 0, v118
	v_and_b32_e32 v119, 0xffff0000, v120
	v_add_f32_e32 v129, v129, v122
	v_lshlrev_b32_e32 v122, 16, v124
	v_add_f32_e32 v131, 0, v119
	v_lshlrev_b32_e32 v120, 16, v121
	v_add_f32_e32 v130, v130, v122
	v_and_b32_e32 v122, 0xffff0000, v124
	v_add_f32_e32 v132, 0, v120
	v_and_b32_e32 v121, 0xffff0000, v121
	v_add_f32_e32 v131, v131, v122
	v_lshlrev_b32_e32 v122, 16, v125
	v_add_f32_e32 v133, 0, v121
	v_add_f32_e32 v132, v132, v122
	v_and_b32_e32 v122, 0xffff0000, v125
	v_add_f32_e32 v133, v133, v122
	v_add_u32_e32 v168, 0x13dc0, v144
	ds_read_b128 v[168:171], v168
	v_add_f32_e32 v126, 0, v114
	v_add_f32_e32 v126, v126, v145
	s_waitcnt lgkmcnt(0)
	v_add_u32_e32 v122, 0x13bb0, v144
	ds_read_b128 v[122:125], v122
	v_add_u32_e32 v172, 0x139a0, v144
	ds_read_b128 v[172:175], v172
	v_lshlrev_b32_e32 v145, 16, v168
	v_and_b32_e32 v168, 0xffff0000, v168
	v_add_f32_e32 v127, v127, v168
	v_lshlrev_b32_e32 v168, 16, v169
	v_add_f32_e32 v128, v128, v168
	v_and_b32_e32 v168, 0xffff0000, v169
	v_add_f32_e32 v129, v129, v168
	v_lshlrev_b32_e32 v168, 16, v170
	v_add_f32_e32 v130, v130, v168
	v_and_b32_e32 v168, 0xffff0000, v170
	v_add_f32_e32 v131, v131, v168
	v_lshlrev_b32_e32 v168, 16, v171
	v_add_f32_e32 v132, v132, v168
	v_and_b32_e32 v168, 0xffff0000, v171
	v_add_f32_e32 v133, v133, v168
	v_add_f32_e32 v126, v126, v145
	s_waitcnt lgkmcnt(1)
	v_add_u32_e32 v168, 0x13790, v144
	ds_read_b128 v[168:171], v168
	v_lshlrev_b32_e32 v145, 16, v122
	v_and_b32_e32 v122, 0xffff0000, v122
	v_add_f32_e32 v127, v127, v122
	v_lshlrev_b32_e32 v122, 16, v123
	v_add_f32_e32 v128, v128, v122
	v_and_b32_e32 v122, 0xffff0000, v123
	v_add_f32_e32 v129, v129, v122
	v_lshlrev_b32_e32 v122, 16, v124
	v_add_f32_e32 v130, v130, v122
	v_and_b32_e32 v122, 0xffff0000, v124
	v_add_f32_e32 v131, v131, v122
	v_lshlrev_b32_e32 v122, 16, v125
	v_add_f32_e32 v132, v132, v122
	v_and_b32_e32 v122, 0xffff0000, v125
	v_add_f32_e32 v133, v133, v122
	v_add_f32_e32 v126, v126, v145
	s_waitcnt lgkmcnt(1)
; __device__ __forceinline__ float bflo(unsigned u) { return __uint_as_float(u << 16); }
; __device__ __forceinline__ float bfhi(unsigned u) { return __uint_as_float(u & 0xffff0000u); }
; template <int W>
; __device__ __forceinline__ void pool_compute(const Params& p, int layer, int g, int dh, int tt, const int tidx) {
;     ...
;       u32x4 x0 = *reinterpret_cast<const u32x4*>(xl + ks * 32);
; #pragma unroll
;       for (int i = 0; i < W; ++i) {
;         u32x4 xv = *reinterpret_cast<const u32x4*>(xl + ks * 32 - i * PXS);
;         sum[0] += bflo(xv.x); sum[1] += bfhi(xv.x); sum[2] += bflo(xv.y); sum[3] += bfhi(xv.y);
;         sum[4] += bflo(xv.z); sum[5] += bfhi(xv.z); sum[6] += bflo(xv.w); sum[7] += bfhi(xv.w);
;       }
	v_add_u32_e32 v122, 0x13580, v144
	ds_read_b128 v[122:125], v122
	v_lshlrev_b32_e32 v145, 16, v172
	v_and_b32_e32 v172, 0xffff0000, v172
	v_add_f32_e32 v127, v127, v172
	v_lshlrev_b32_e32 v172, 16, v173
	v_add_f32_e32 v128, v128, v172
	v_and_b32_e32 v172, 0xffff0000, v173
	v_add_f32_e32 v129, v129, v172
	v_lshlrev_b32_e32 v172, 16, v174
	v_add_f32_e32 v130, v130, v172
	v_and_b32_e32 v172, 0xffff0000, v174
	v_add_f32_e32 v131, v131, v172
	v_lshlrev_b32_e32 v172, 16, v175
	v_add_f32_e32 v132, v132, v172
	v_and_b32_e32 v172, 0xffff0000, v175
	v_add_f32_e32 v133, v133, v172
	v_add_f32_e32 v126, v126, v145
	s_waitcnt lgkmcnt(1)
	v_add_u32_e32 v172, 0x13370, v144
	ds_read_b128 v[172:175], v172
	v_lshlrev_b32_e32 v145, 16, v168
	v_and_b32_e32 v168, 0xffff0000, v168
	v_add_f32_e32 v127, v127, v168
	v_lshlrev_b32_e32 v168, 16, v169
	v_add_f32_e32 v128, v128, v168
	v_and_b32_e32 v168, 0xffff0000, v169
	v_add_f32_e32 v129, v129, v168
	v_lshlrev_b32_e32 v168, 16, v170
	v_add_f32_e32 v130, v130, v168
	v_and_b32_e32 v168, 0xffff0000, v170
	v_add_f32_e32 v131, v131, v168
	v_lshlrev_b32_e32 v168, 16, v171
	v_add_f32_e32 v132, v132, v168
	v_and_b32_e32 v168, 0xffff0000, v171
	v_add_f32_e32 v133, v133, v168
	v_add_f32_e32 v126, v126, v145
	s_waitcnt lgkmcnt(1)
	v_add_u32_e32 v168, 0x13160, v144
	ds_read_b128 v[168:171], v168
	v_lshlrev_b32_e32 v145, 16, v122
	v_and_b32_e32 v122, 0xffff0000, v122
	v_add_f32_e32 v127, v127, v122
	v_lshlrev_b32_e32 v122, 16, v123
	v_add_f32_e32 v128, v128, v122
	v_and_b32_e32 v122, 0xffff0000, v123
	v_add_f32_e32 v129, v129, v122
	v_lshlrev_b32_e32 v122, 16, v124
	v_add_f32_e32 v130, v130, v122
	v_and_b32_e32 v122, 0xffff0000, v124
	v_add_f32_e32 v131, v131, v122
	v_lshlrev_b32_e32 v122, 16, v125
	v_add_f32_e32 v132, v132, v122
	v_and_b32_e32 v122, 0xffff0000, v125
	v_add_f32_e32 v133, v133, v122
	v_add_f32_e32 v126, v126, v145
	s_waitcnt lgkmcnt(1)
	v_add_u32_e32 v122, 0x12f50, v144
	ds_read_b128 v[122:125], v122
	v_lshlrev_b32_e32 v145, 16, v172
	v_and_b32_e32 v172, 0xffff0000, v172
	v_add_f32_e32 v127, v127, v172
	v_lshlrev_b32_e32 v172, 16, v173
	v_add_f32_e32 v128, v128, v172
	v_and_b32_e32 v172, 0xffff0000, v173
	v_add_f32_e32 v129, v129, v172
	v_lshlrev_b32_e32 v172, 16, v174
	v_add_f32_e32 v130, v130, v172
	v_and_b32_e32 v172, 0xffff0000, v174
	v_add_f32_e32 v131, v131, v172
	v_lshlrev_b32_e32 v172, 16, v175
	v_add_f32_e32 v132, v132, v172
	v_and_b32_e32 v172, 0xffff0000, v175
	v_add_f32_e32 v133, v133, v172
	v_add_f32_e32 v126, v126, v145
	s_waitcnt lgkmcnt(1)
	v_add_u32_e32 v172, 0x12d40, v144
	ds_read_b128 v[172:175], v172
	v_lshlrev_b32_e32 v145, 16, v168
	v_and_b32_e32 v168, 0xffff0000, v168
	v_add_f32_e32 v127, v127, v168
	v_lshlrev_b32_e32 v168, 16, v169
	v_add_f32_e32 v128, v128, v168
	v_and_b32_e32 v168, 0xffff0000, v169
	v_add_f32_e32 v129, v129, v168
	v_lshlrev_b32_e32 v168, 16, v170
	v_add_f32_e32 v130, v130, v168
	v_and_b32_e32 v168, 0xffff0000, v170
	v_add_f32_e32 v131, v131, v168
	v_lshlrev_b32_e32 v168, 16, v171
	v_add_f32_e32 v132, v132, v168
	v_and_b32_e32 v168, 0xffff0000, v171
	v_add_f32_e32 v133, v133, v168
	v_add_f32_e32 v126, v126, v145
	s_waitcnt lgkmcnt(1)
	v_add_u32_e32 v168, 0x12b30, v144
	ds_read_b128 v[168:171], v168
	v_lshlrev_b32_e32 v145, 16, v122
	v_and_b32_e32 v122, 0xffff0000, v122
	v_add_f32_e32 v127, v127, v122
	v_lshlrev_b32_e32 v122, 16, v123
	v_add_f32_e32 v128, v128, v122
	v_and_b32_e32 v122, 0xffff0000, v123
	v_add_f32_e32 v129, v129, v122
	v_lshlrev_b32_e32 v122, 16, v124
	v_add_f32_e32 v130, v130, v122
	v_and_b32_e32 v122, 0xffff0000, v124
	v_add_f32_e32 v131, v131, v122
	v_lshlrev_b32_e32 v122, 16, v125
	v_add_f32_e32 v132, v132, v122
	v_and_b32_e32 v122, 0xffff0000, v125
	v_add_f32_e32 v133, v133, v122
	v_add_f32_e32 v126, v126, v145
	s_waitcnt lgkmcnt(1)
	v_add_u32_e32 v122, 0x12920, v144
	ds_read_b128 v[122:125], v122
	v_lshlrev_b32_e32 v145, 16, v172
	v_and_b32_e32 v172, 0xffff0000, v172
	v_add_f32_e32 v127, v127, v172
	v_lshlrev_b32_e32 v172, 16, v173
	v_add_f32_e32 v128, v128, v172
	v_and_b32_e32 v172, 0xffff0000, v173
	v_add_f32_e32 v129, v129, v172
	v_lshlrev_b32_e32 v172, 16, v174
	v_add_f32_e32 v130, v130, v172
	v_and_b32_e32 v172, 0xffff0000, v174
	v_add_f32_e32 v131, v131, v172
	v_lshlrev_b32_e32 v172, 16, v175
	v_add_f32_e32 v132, v132, v172
	v_and_b32_e32 v172, 0xffff0000, v175
	v_add_f32_e32 v133, v133, v172
	v_add_f32_e32 v126, v126, v145
	s_waitcnt lgkmcnt(1)
	v_add_u32_e32 v172, 0x12710, v144
	ds_read_b128 v[172:175], v172
	v_lshlrev_b32_e32 v145, 16, v168
	v_and_b32_e32 v168, 0xffff0000, v168
	v_add_f32_e32 v127, v127, v168
	v_lshlrev_b32_e32 v168, 16, v169
	v_add_f32_e32 v128, v128, v168
	v_and_b32_e32 v168, 0xffff0000, v169
	v_add_f32_e32 v129, v129, v168
	v_lshlrev_b32_e32 v168, 16, v170
	v_add_f32_e32 v130, v130, v168
	v_and_b32_e32 v168, 0xffff0000, v170
	v_add_f32_e32 v131, v131, v168
	v_lshlrev_b32_e32 v168, 16, v171
	v_add_f32_e32 v132, v132, v168
	v_and_b32_e32 v168, 0xffff0000, v171
	v_add_f32_e32 v133, v133, v168
	v_add_f32_e32 v126, v126, v145
	s_waitcnt lgkmcnt(1)
	v_add_u32_e32 v168, 0x12500, v144
	ds_read_b128 v[168:171], v168
	v_lshlrev_b32_e32 v145, 16, v122
	v_and_b32_e32 v122, 0xffff0000, v122
	v_add_f32_e32 v127, v127, v122
	v_lshlrev_b32_e32 v122, 16, v123
	v_add_f32_e32 v128, v128, v122
	v_and_b32_e32 v122, 0xffff0000, v123
	v_add_f32_e32 v129, v129, v122
	v_lshlrev_b32_e32 v122, 16, v124
	v_add_f32_e32 v130, v130, v122
	v_and_b32_e32 v122, 0xffff0000, v124
	v_add_f32_e32 v131, v131, v122
	v_lshlrev_b32_e32 v122, 16, v125
	v_add_f32_e32 v132, v132, v122
	v_and_b32_e32 v122, 0xffff0000, v125
	v_add_f32_e32 v133, v133, v122
	v_add_f32_e32 v126, v126, v145
	s_waitcnt lgkmcnt(1)
; __device__ __forceinline__ float bflo(unsigned u) { return __uint_as_float(u << 16); }
; __device__ __forceinline__ float bfhi(unsigned u) { return __uint_as_float(u & 0xffff0000u); }
; template <int W>
; __device__ __forceinline__ void pool_compute(const Params& p, int layer, int g, int dh, int tt, const int tidx) {
;     ...
;       u32x4 x0 = *reinterpret_cast<const u32x4*>(xl + ks * 32);
; #pragma unroll
;       for (int i = 0; i < W; ++i) {
;         u32x4 xv = *reinterpret_cast<const u32x4*>(xl + ks * 32 - i * PXS);
;         sum[0] += bflo(xv.x); sum[1] += bfhi(xv.x); sum[2] += bflo(xv.y); sum[3] += bfhi(xv.y);
;         sum[4] += bflo(xv.z); sum[5] += bfhi(xv.z); sum[6] += bflo(xv.w); sum[7] += bfhi(xv.w);
;       }
;       u32x4 bfr;
;       bfr.x = pack2(sum[0] * inv - bflo(x0.x), sum[1] * inv - bfhi(x0.x));
;       bfr.y = pack2(sum[2] * inv - bflo(x0.y), sum[3] * inv - bfhi(x0.y));
;       bfr.z = pack2(sum[4] * inv - bflo(x0.z), sum[5] * inv - bfhi(x0.z));
;       bfr.w = pack2(sum[6] * inv - bflo(x0.w), sum[7] * inv - bfhi(x0.w));
; #pragma unroll
;       for (int d = 0; d < 4; ++d) acc[d] = __builtin_amdgcn_mfma_f32_32x32x16_bf16(as_bf16x8(av[k4][d]), as_bf16x8(bfr), acc[d], 0, 0, 0);
;     }
	v_add_u32_e32 v122, 0x122f0, v144
	ds_read_b128 v[122:125], v122
	v_lshlrev_b32_e32 v145, 16, v172
	v_and_b32_e32 v172, 0xffff0000, v172
	v_add_f32_e32 v127, v127, v172
	v_lshlrev_b32_e32 v172, 16, v173
	v_add_f32_e32 v128, v128, v172
	v_and_b32_e32 v172, 0xffff0000, v173
	v_add_f32_e32 v129, v129, v172
	v_lshlrev_b32_e32 v172, 16, v174
	v_add_f32_e32 v130, v130, v172
	v_and_b32_e32 v172, 0xffff0000, v174
	v_add_f32_e32 v131, v131, v172
	v_lshlrev_b32_e32 v172, 16, v175
	v_add_f32_e32 v132, v132, v172
	v_and_b32_e32 v172, 0xffff0000, v175
	v_add_f32_e32 v133, v133, v172
	v_add_f32_e32 v126, v126, v145
	s_waitcnt lgkmcnt(1)
	v_lshlrev_b32_e32 v145, 16, v168
	v_and_b32_e32 v168, 0xffff0000, v168
	v_add_f32_e32 v127, v127, v168
	v_lshlrev_b32_e32 v168, 16, v169
	v_add_f32_e32 v128, v128, v168
	v_and_b32_e32 v168, 0xffff0000, v169
	v_add_f32_e32 v129, v129, v168
	v_lshlrev_b32_e32 v168, 16, v170
	v_add_f32_e32 v130, v130, v168
	v_and_b32_e32 v168, 0xffff0000, v170
	v_add_f32_e32 v131, v131, v168
	v_lshlrev_b32_e32 v168, 16, v171
	v_add_f32_e32 v132, v132, v168
	v_and_b32_e32 v168, 0xffff0000, v171
	v_add_f32_e32 v133, v133, v168
	v_add_f32_e32 v126, v126, v145
	s_waitcnt lgkmcnt(0)
	v_lshlrev_b32_e32 v145, 16, v122
	v_and_b32_e32 v122, 0xffff0000, v122
	v_add_f32_e32 v126, v126, v145
	v_add_f32_e32 v122, v127, v122
	v_lshlrev_b32_e32 v127, 16, v123
	v_and_b32_e32 v123, 0xffff0000, v123
	v_add_f32_e32 v127, v128, v127
	v_add_f32_e32 v123, v129, v123
	v_lshlrev_b32_e32 v128, 16, v124
	v_and_b32_e32 v124, 0xffff0000, v124
	v_fma_f32 v114, v135, v126, -v114
	v_fma_f32 v115, v135, v122, -v115
	v_add_f32_e32 v128, v130, v128
	v_add_f32_e32 v124, v131, v124
	v_lshlrev_b32_e32 v129, 16, v125
	v_cvt_pk_bf16_f32 v114, v114, v115
	v_fma_f32 v115, v135, v127, -v116
	v_fma_f32 v116, v135, v123, -v117
	v_add_f32_e32 v129, v132, v129
	v_and_b32_e32 v125, 0xffff0000, v125
	v_cvt_pk_bf16_f32 v115, v115, v116
	v_fma_f32 v116, v135, v128, -v118
	v_fma_f32 v117, v135, v124, -v119
	v_add_f32_e32 v125, v133, v125
	v_cvt_pk_bf16_f32 v116, v116, v117
	v_fma_f32 v117, v135, v129, -v120
	v_fma_f32 v118, v135, v125, -v121
	v_cvt_pk_bf16_f32 v117, v117, v118
	s_nop 0
	v_mfma_f32_32x32x16_bf16 v[48:63], v[98:101], v[114:117], v[48:63]
	v_add_u32_e32 v98, 0x14200, v144
	v_mfma_f32_32x32x16_bf16 v[32:47], v[102:105], v[114:117], v[32:47]
	ds_read_b128 v[102:105], v98
	v_mfma_f32_32x32x16_bf16 v[16:31], v[106:109], v[114:117], v[16:31]
	v_add_u32_e32 v106, 0x13ff0, v144
	ds_read_b128 v[106:109], v106
	s_waitcnt lgkmcnt(1)
	v_and_b32_e32 v99, 0xffff0000, v102
	v_lshlrev_b32_e32 v100, 16, v103
	v_and_b32_e32 v101, 0xffff0000, v103
	v_lshlrev_b32_e32 v98, 16, v102
	s_waitcnt lgkmcnt(0)
	v_lshlrev_b32_e32 v118, 16, v106
	s_waitcnt vmcnt(8)
	v_mfma_f32_32x32x16_bf16 v[0:15], v[110:113], v[114:117], v[0:15]
	v_add_f32_e32 v111, 0, v99
	v_and_b32_e32 v106, 0xffff0000, v106
	v_add_f32_e32 v112, 0, v100
	v_add_f32_e32 v111, v111, v106
	v_lshlrev_b32_e32 v106, 16, v107
	v_add_f32_e32 v113, 0, v101
	v_lshlrev_b32_e32 v102, 16, v104
	v_add_f32_e32 v112, v112, v106
	v_and_b32_e32 v106, 0xffff0000, v107
	v_add_f32_e32 v114, 0, v102
	v_and_b32_e32 v103, 0xffff0000, v104
	v_add_f32_e32 v113, v113, v106
	v_lshlrev_b32_e32 v106, 16, v108
	v_add_f32_e32 v115, 0, v103
	v_lshlrev_b32_e32 v104, 16, v105
	v_add_f32_e32 v114, v114, v106
	v_and_b32_e32 v106, 0xffff0000, v108
	v_add_f32_e32 v116, 0, v104
	v_and_b32_e32 v105, 0xffff0000, v105
	v_add_f32_e32 v115, v115, v106
	v_lshlrev_b32_e32 v106, 16, v109
	v_add_f32_e32 v117, 0, v105
	v_add_f32_e32 v116, v116, v106
	v_and_b32_e32 v106, 0xffff0000, v109
	v_add_f32_e32 v117, v117, v106
	v_add_u32_e32 v168, 0x13de0, v144
	ds_read_b128 v[168:171], v168
	v_add_f32_e32 v110, 0, v98
	v_add_f32_e32 v110, v110, v118
	s_waitcnt lgkmcnt(0)
	v_add_u32_e32 v106, 0x13bd0, v144
	ds_read_b128 v[106:109], v106
	v_add_u32_e32 v172, 0x139c0, v144
	ds_read_b128 v[172:175], v172
	v_lshlrev_b32_e32 v118, 16, v168
	v_and_b32_e32 v168, 0xffff0000, v168
	v_add_f32_e32 v111, v111, v168
	v_lshlrev_b32_e32 v168, 16, v169
	v_add_f32_e32 v112, v112, v168
	v_and_b32_e32 v168, 0xffff0000, v169
	v_add_f32_e32 v113, v113, v168
	v_lshlrev_b32_e32 v168, 16, v170
	v_add_f32_e32 v114, v114, v168
	v_and_b32_e32 v168, 0xffff0000, v170
	v_add_f32_e32 v115, v115, v168
	v_lshlrev_b32_e32 v168, 16, v171
	v_add_f32_e32 v116, v116, v168
	v_and_b32_e32 v168, 0xffff0000, v171
	v_add_f32_e32 v117, v117, v168
	v_add_f32_e32 v110, v110, v118
	s_waitcnt lgkmcnt(1)
	v_add_u32_e32 v168, 0x137b0, v144
	ds_read_b128 v[168:171], v168
	v_lshlrev_b32_e32 v118, 16, v106
	v_and_b32_e32 v106, 0xffff0000, v106
	v_add_f32_e32 v111, v111, v106
	v_lshlrev_b32_e32 v106, 16, v107
	v_add_f32_e32 v112, v112, v106
	v_and_b32_e32 v106, 0xffff0000, v107
	v_add_f32_e32 v113, v113, v106
	v_lshlrev_b32_e32 v106, 16, v108
	v_add_f32_e32 v114, v114, v106
	v_and_b32_e32 v106, 0xffff0000, v108
	v_add_f32_e32 v115, v115, v106
	v_lshlrev_b32_e32 v106, 16, v109
	v_add_f32_e32 v116, v116, v106
	v_and_b32_e32 v106, 0xffff0000, v109
	v_add_f32_e32 v117, v117, v106
	v_add_f32_e32 v110, v110, v118
	s_waitcnt lgkmcnt(1)
	v_add_u32_e32 v106, 0x135a0, v144
	ds_read_b128 v[106:109], v106
	v_lshlrev_b32_e32 v118, 16, v172
	v_and_b32_e32 v172, 0xffff0000, v172
	v_add_f32_e32 v111, v111, v172
	v_lshlrev_b32_e32 v172, 16, v173
	v_add_f32_e32 v112, v112, v172
	v_and_b32_e32 v172, 0xffff0000, v173
	v_add_f32_e32 v113, v113, v172
	v_lshlrev_b32_e32 v172, 16, v174
	v_add_f32_e32 v114, v114, v172
	v_and_b32_e32 v172, 0xffff0000, v174
	v_add_f32_e32 v115, v115, v172
	v_lshlrev_b32_e32 v172, 16, v175
	v_add_f32_e32 v116, v116, v172
	v_and_b32_e32 v172, 0xffff0000, v175
	v_add_f32_e32 v117, v117, v172
	v_add_f32_e32 v110, v110, v118
	s_waitcnt lgkmcnt(1)
; __device__ __forceinline__ float bflo(unsigned u) { return __uint_as_float(u << 16); }
; __device__ __forceinline__ float bfhi(unsigned u) { return __uint_as_float(u & 0xffff0000u); }
; template <int W>
; __device__ __forceinline__ void pool_compute(const Params& p, int layer, int g, int dh, int tt, const int tidx) {
;     ...
;       u32x4 x0 = *reinterpret_cast<const u32x4*>(xl + ks * 32);
; #pragma unroll
;       for (int i = 0; i < W; ++i) {
;         u32x4 xv = *reinterpret_cast<const u32x4*>(xl + ks * 32 - i * PXS);
;         sum[0] += bflo(xv.x); sum[1] += bfhi(xv.x); sum[2] += bflo(xv.y); sum[3] += bfhi(xv.y);
;         sum[4] += bflo(xv.z); sum[5] += bfhi(xv.z); sum[6] += bflo(xv.w); sum[7] += bfhi(xv.w);
;       }
	v_lshlrev_b32_e32 v118, 16, v168
	v_and_b32_e32 v168, 0xffff0000, v168
	v_add_f32_e32 v111, v111, v168
	v_lshlrev_b32_e32 v168, 16, v169
	v_add_f32_e32 v112, v112, v168
	v_and_b32_e32 v168, 0xffff0000, v169
	v_add_f32_e32 v113, v113, v168
	v_lshlrev_b32_e32 v168, 16, v170
	v_add_f32_e32 v114, v114, v168
	v_and_b32_e32 v168, 0xffff0000, v170
	v_add_f32_e32 v115, v115, v168
	v_lshlrev_b32_e32 v168, 16, v171
	v_add_f32_e32 v116, v116, v168
	v_and_b32_e32 v168, 0xffff0000, v171
	v_add_f32_e32 v117, v117, v168
	v_add_f32_e32 v110, v110, v118
	s_waitcnt lgkmcnt(0)
	v_lshlrev_b32_e32 v118, 16, v106
	v_and_b32_e32 v106, 0xffff0000, v106
	v_add_f32_e32 v119, v111, v106
	v_lshlrev_b32_e32 v106, 16, v107
	v_add_f32_e32 v120, v112, v106
	v_and_b32_e32 v106, 0xffff0000, v107
	v_add_f32_e32 v121, v113, v106
	v_lshlrev_b32_e32 v106, 16, v108
	v_add_f32_e32 v114, v114, v106
	v_and_b32_e32 v106, 0xffff0000, v108
	v_add_f32_e32 v115, v115, v106
	v_lshlrev_b32_e32 v106, 16, v109
	v_add_f32_e32 v116, v116, v106
	v_and_b32_e32 v106, 0xffff0000, v109
	v_add_f32_e32 v117, v117, v106
	v_add_u32_e32 v106, 0x13390, v144
	v_add_f32_e32 v118, v110, v118
	ds_read_b128 v[110:113], v106
	s_waitcnt lgkmcnt(0)
	v_lshlrev_b32_e32 v106, 16, v110
	v_and_b32_e32 v107, 0xffff0000, v110
	v_lshlrev_b32_e32 v110, 16, v112
	v_lshlrev_b32_e32 v108, 16, v111
	v_and_b32_e32 v109, 0xffff0000, v111
	v_add_f32_e32 v110, v114, v110
	v_and_b32_e32 v111, 0xffff0000, v112
	v_lshlrev_b32_e32 v112, 16, v113
	v_and_b32_e32 v113, 0xffff0000, v113
	v_add_u32_e32 v114, 0x13180, v144
	v_add_f32_e32 v111, v115, v111
	v_add_f32_e32 v112, v116, v112
	v_add_f32_e32 v113, v117, v113
	ds_read_b128 v[114:117], v114
	v_add_f32_e32 v106, v118, v106
	v_add_f32_e32 v107, v119, v107
	v_add_f32_e32 v108, v120, v108
	v_add_f32_e32 v109, v121, v109
	s_waitcnt lgkmcnt(0)
	v_lshlrev_b32_e32 v118, 16, v114
	v_add_f32_e32 v118, v106, v118
	v_and_b32_e32 v106, 0xffff0000, v114
	v_add_f32_e32 v114, v107, v106
	v_lshlrev_b32_e32 v106, 16, v115
	v_add_f32_e32 v119, v108, v106
	v_and_b32_e32 v106, 0xffff0000, v115
	v_add_f32_e32 v115, v109, v106
	v_lshlrev_b32_e32 v106, 16, v116
	v_add_f32_e32 v110, v110, v106
	v_and_b32_e32 v106, 0xffff0000, v116
	v_add_f32_e32 v111, v111, v106
	v_lshlrev_b32_e32 v106, 16, v117
	v_add_f32_e32 v112, v112, v106
	v_and_b32_e32 v106, 0xffff0000, v117
	v_add_f32_e32 v113, v113, v106
	v_add_u32_e32 v106, 0x12f70, v144
	ds_read_b128 v[106:109], v106
	s_waitcnt lgkmcnt(0)
	v_add_u32_e32 v172, 0x12d60, v144
	ds_read_b128 v[172:175], v172
	v_add_u32_e32 v168, 0x12b50, v144
	ds_read_b128 v[168:171], v168
	v_lshlrev_b32_e32 v116, 16, v106
	v_and_b32_e32 v106, 0xffff0000, v106
	v_add_f32_e32 v114, v114, v106
	v_lshlrev_b32_e32 v106, 16, v107
	v_add_f32_e32 v117, v119, v106
	v_and_b32_e32 v106, 0xffff0000, v107
	v_add_f32_e32 v115, v115, v106
	v_lshlrev_b32_e32 v106, 16, v108
	v_add_f32_e32 v110, v110, v106
	v_and_b32_e32 v106, 0xffff0000, v108
	v_add_f32_e32 v111, v111, v106
	v_lshlrev_b32_e32 v106, 16, v109
	v_add_f32_e32 v112, v112, v106
	v_and_b32_e32 v106, 0xffff0000, v109
	v_add_f32_e32 v113, v113, v106
	v_add_f32_e32 v116, v118, v116
	s_waitcnt lgkmcnt(1)
	v_add_u32_e32 v106, 0x12940, v144
	ds_read_b128 v[106:109], v106
	v_lshlrev_b32_e32 v118, 16, v172
	v_and_b32_e32 v172, 0xffff0000, v172
	v_add_f32_e32 v114, v114, v172
	v_lshlrev_b32_e32 v172, 16, v173
	v_add_f32_e32 v117, v117, v172
	v_and_b32_e32 v172, 0xffff0000, v173
	v_add_f32_e32 v115, v115, v172
	v_lshlrev_b32_e32 v172, 16, v174
	v_add_f32_e32 v110, v110, v172
	v_and_b32_e32 v172, 0xffff0000, v174
	v_add_f32_e32 v111, v111, v172
	v_lshlrev_b32_e32 v172, 16, v175
	v_add_f32_e32 v112, v112, v172
	v_and_b32_e32 v172, 0xffff0000, v175
	v_add_f32_e32 v113, v113, v172
	v_add_f32_e32 v116, v116, v118
	s_waitcnt lgkmcnt(1)
	v_add_u32_e32 v172, 0x12730, v144
	ds_read_b128 v[172:175], v172
	v_lshlrev_b32_e32 v118, 16, v168
	v_and_b32_e32 v168, 0xffff0000, v168
	v_add_f32_e32 v114, v114, v168
	v_lshlrev_b32_e32 v168, 16, v169
	v_add_f32_e32 v117, v117, v168
	v_and_b32_e32 v168, 0xffff0000, v169
	v_add_f32_e32 v115, v115, v168
	v_lshlrev_b32_e32 v168, 16, v170
	v_add_f32_e32 v110, v110, v168
	v_and_b32_e32 v168, 0xffff0000, v170
	v_add_f32_e32 v111, v111, v168
	v_lshlrev_b32_e32 v168, 16, v171
	v_add_f32_e32 v112, v112, v168
	v_and_b32_e32 v168, 0xffff0000, v171
	v_add_f32_e32 v113, v113, v168
	v_add_f32_e32 v116, v116, v118
	s_waitcnt lgkmcnt(1)
	v_add_u32_e32 v168, 0x12520, v144
	ds_read_b128 v[168:171], v168
	v_lshlrev_b32_e32 v118, 16, v106
	v_and_b32_e32 v106, 0xffff0000, v106
	v_add_f32_e32 v114, v114, v106
	v_lshlrev_b32_e32 v106, 16, v107
	v_add_f32_e32 v117, v117, v106
	v_and_b32_e32 v106, 0xffff0000, v107
	v_add_f32_e32 v115, v115, v106
	v_lshlrev_b32_e32 v106, 16, v108
	v_add_f32_e32 v110, v110, v106
	v_and_b32_e32 v106, 0xffff0000, v108
	v_add_f32_e32 v111, v111, v106
	v_lshlrev_b32_e32 v106, 16, v109
	v_add_f32_e32 v112, v112, v106
	v_and_b32_e32 v106, 0xffff0000, v109
	v_add_f32_e32 v113, v113, v106
	v_add_f32_e32 v116, v116, v118
	s_waitcnt lgkmcnt(1)
	v_add_u32_e32 v106, 0x12310, v144
	ds_read_b128 v[106:109], v106
	v_lshlrev_b32_e32 v118, 16, v172
	v_and_b32_e32 v172, 0xffff0000, v172
	v_add_f32_e32 v114, v114, v172
	v_lshlrev_b32_e32 v172, 16, v173
	v_add_f32_e32 v117, v117, v172
	v_and_b32_e32 v172, 0xffff0000, v173
	v_add_f32_e32 v115, v115, v172
	v_lshlrev_b32_e32 v172, 16, v174
	v_add_f32_e32 v110, v110, v172
	v_and_b32_e32 v172, 0xffff0000, v174
	v_add_f32_e32 v111, v111, v172
	v_lshlrev_b32_e32 v172, 16, v175
	v_add_f32_e32 v112, v112, v172
	v_and_b32_e32 v172, 0xffff0000, v175
	v_add_f32_e32 v113, v113, v172
	v_add_f32_e32 v116, v116, v118
	s_waitcnt lgkmcnt(1)
; __device__ __forceinline__ float bflo(unsigned u) { return __uint_as_float(u << 16); }
; __device__ __forceinline__ float bfhi(unsigned u) { return __uint_as_float(u & 0xffff0000u); }
; template <int W>
; __device__ __forceinline__ void pool_compute(const Params& p, int layer, int g, int dh, int tt, const int tidx) {
;     ...
;     for (int k4 = 0; k4 < 4; ++k4) {
;       const int ks = kb * 4 + k4;
;       float sum[8];
; #pragma unroll
;       for (int j = 0; j < 8; ++j) sum[j] = 0.f;
;       u32x4 x0 = *reinterpret_cast<const u32x4*>(xl + ks * 32);
; #pragma unroll
;       for (int i = 0; i < W; ++i) {
;         u32x4 xv = *reinterpret_cast<const u32x4*>(xl + ks * 32 - i * PXS);
;         sum[0] += bflo(xv.x); sum[1] += bfhi(xv.x); sum[2] += bflo(xv.y); sum[3] += bfhi(xv.y);
;         sum[4] += bflo(xv.z); sum[5] += bfhi(xv.z); sum[6] += bflo(xv.w); sum[7] += bfhi(xv.w);
;       }
;       u32x4 bfr;
;       bfr.x = pack2(sum[0] * inv - bflo(x0.x), sum[1] * inv - bfhi(x0.x));
;       bfr.y = pack2(sum[2] * inv - bflo(x0.y), sum[3] * inv - bfhi(x0.y));
;       bfr.z = pack2(sum[4] * inv - bflo(x0.z), sum[5] * inv - bfhi(x0.z));
;       bfr.w = pack2(sum[6] * inv - bflo(x0.w), sum[7] * inv - bfhi(x0.w));
; #pragma unroll
;       for (int d = 0; d < 4; ++d) acc[d] = __builtin_amdgcn_mfma_f32_32x32x16_bf16(as_bf16x8(av[k4][d]), as_bf16x8(bfr), acc[d], 0, 0, 0);
;     }
	v_lshlrev_b32_e32 v118, 16, v168
	v_and_b32_e32 v168, 0xffff0000, v168
	v_add_f32_e32 v114, v114, v168
	v_lshlrev_b32_e32 v168, 16, v169
	v_add_f32_e32 v117, v117, v168
	v_and_b32_e32 v168, 0xffff0000, v169
	v_add_f32_e32 v115, v115, v168
	v_lshlrev_b32_e32 v168, 16, v170
	v_add_f32_e32 v110, v110, v168
	v_and_b32_e32 v168, 0xffff0000, v170
	v_add_f32_e32 v111, v111, v168
	v_lshlrev_b32_e32 v168, 16, v171
	v_add_f32_e32 v112, v112, v168
	v_and_b32_e32 v168, 0xffff0000, v171
	v_add_f32_e32 v113, v113, v168
	v_add_f32_e32 v116, v116, v118
	s_waitcnt lgkmcnt(0)
	v_lshlrev_b32_e32 v118, 16, v106
	v_and_b32_e32 v106, 0xffff0000, v106
	v_add_f32_e32 v116, v116, v118
	v_add_f32_e32 v106, v114, v106
	v_lshlrev_b32_e32 v114, 16, v107
	v_and_b32_e32 v107, 0xffff0000, v107
	v_add_f32_e32 v114, v117, v114
	v_add_f32_e32 v107, v115, v107
	v_lshlrev_b32_e32 v115, 16, v108
	v_and_b32_e32 v108, 0xffff0000, v108
	v_fma_f32 v98, v135, v116, -v98
	v_fma_f32 v99, v135, v106, -v99
	v_add_f32_e32 v110, v110, v115
	v_add_f32_e32 v108, v111, v108
	v_lshlrev_b32_e32 v111, 16, v109
	v_cvt_pk_bf16_f32 v98, v98, v99
	v_fma_f32 v99, v135, v114, -v100
	v_fma_f32 v100, v135, v107, -v101
	v_add_f32_e32 v111, v112, v111
	v_and_b32_e32 v109, 0xffff0000, v109
	v_cvt_pk_bf16_f32 v99, v99, v100
	v_fma_f32 v100, v135, v110, -v102
	v_fma_f32 v101, v135, v108, -v103
	v_add_f32_e32 v109, v113, v109
	v_cvt_pk_bf16_f32 v100, v100, v101
	v_fma_f32 v101, v135, v111, -v104
	v_fma_f32 v102, v135, v109, -v105
	v_cvt_pk_bf16_f32 v101, v101, v102
	s_waitcnt vmcnt(7)
	v_mfma_f32_32x32x16_bf16 v[48:63], v[80:83], v[98:101], v[48:63]
	v_add_u32_e32 v80, 0x14220, v144
	s_waitcnt vmcnt(3)
	v_mfma_f32_32x32x16_bf16 v[16:31], v[88:91], v[98:101], v[16:31]
	ds_read_b128 v[88:91], v80
	s_waitcnt lgkmcnt(0)
	v_lshlrev_b32_e32 v83, 16, v90
	v_and_b32_e32 v82, 0xffff0000, v90
	v_mfma_f32_32x32x16_bf16 v[32:47], v[84:87], v[98:101], v[32:47]
	v_lshlrev_b32_e32 v86, 16, v88
	v_and_b32_e32 v87, 0xffff0000, v88
	v_add_u32_e32 v88, 0x14010, v144
	v_lshlrev_b32_e32 v84, 16, v89
	v_and_b32_e32 v85, 0xffff0000, v89
	v_lshlrev_b32_e32 v80, 16, v91
	v_and_b32_e32 v81, 0xffff0000, v91
	ds_read_b128 v[88:91], v88
	s_waitcnt vmcnt(1)
	v_mfma_f32_32x32x16_bf16 v[0:15], v[92:95], v[98:101], v[0:15]
	v_add_f32_e32 v93, 0, v87
	v_add_f32_e32 v94, 0, v84
	v_add_f32_e32 v95, 0, v85
	s_waitcnt lgkmcnt(0)
	v_lshlrev_b32_e32 v102, 16, v88
	v_and_b32_e32 v88, 0xffff0000, v88
	v_add_f32_e32 v93, v93, v88
	v_lshlrev_b32_e32 v88, 16, v89
	v_add_f32_e32 v94, v94, v88
	v_and_b32_e32 v88, 0xffff0000, v89
	v_add_f32_e32 v98, 0, v83
	v_add_f32_e32 v95, v95, v88
	v_lshlrev_b32_e32 v88, 16, v90
	v_add_f32_e32 v99, 0, v82
	v_add_f32_e32 v98, v98, v88
	v_and_b32_e32 v88, 0xffff0000, v90
	v_add_f32_e32 v100, 0, v80
	v_add_f32_e32 v99, v99, v88
	v_lshlrev_b32_e32 v88, 16, v91
	v_add_f32_e32 v101, 0, v81
	v_add_f32_e32 v100, v100, v88
	v_and_b32_e32 v88, 0xffff0000, v91
	v_add_f32_e32 v101, v101, v88
	v_add_u32_e32 v168, 0x13e00, v144
	ds_read_b128 v[168:171], v168
	v_add_f32_e32 v92, 0, v86
	v_add_f32_e32 v92, v92, v102
	s_waitcnt lgkmcnt(0)
	v_add_u32_e32 v88, 0x13bf0, v144
	ds_read_b128 v[88:91], v88
	v_add_u32_e32 v172, 0x139e0, v144
	ds_read_b128 v[172:175], v172
	v_lshlrev_b32_e32 v102, 16, v168
	v_and_b32_e32 v168, 0xffff0000, v168
	v_add_f32_e32 v93, v93, v168
	v_lshlrev_b32_e32 v168, 16, v169
	v_add_f32_e32 v94, v94, v168
	v_and_b32_e32 v168, 0xffff0000, v169
	v_add_f32_e32 v95, v95, v168
	v_lshlrev_b32_e32 v168, 16, v170
	v_add_f32_e32 v98, v98, v168
	v_and_b32_e32 v168, 0xffff0000, v170
	v_add_f32_e32 v99, v99, v168
	v_lshlrev_b32_e32 v168, 16, v171
	v_add_f32_e32 v100, v100, v168
	v_and_b32_e32 v168, 0xffff0000, v171
	v_add_f32_e32 v101, v101, v168
	v_add_f32_e32 v92, v92, v102
	s_waitcnt lgkmcnt(1)
	v_add_u32_e32 v168, 0x137d0, v144
	ds_read_b128 v[168:171], v168
	v_lshlrev_b32_e32 v102, 16, v88
	v_and_b32_e32 v88, 0xffff0000, v88
	v_add_f32_e32 v93, v93, v88
	v_lshlrev_b32_e32 v88, 16, v89
	v_add_f32_e32 v94, v94, v88
	v_and_b32_e32 v88, 0xffff0000, v89
	v_add_f32_e32 v95, v95, v88
	v_lshlrev_b32_e32 v88, 16, v90
	v_add_f32_e32 v98, v98, v88
	v_and_b32_e32 v88, 0xffff0000, v90
	v_add_f32_e32 v99, v99, v88
	v_lshlrev_b32_e32 v88, 16, v91
	v_add_f32_e32 v100, v100, v88
	v_and_b32_e32 v88, 0xffff0000, v91
	v_add_f32_e32 v101, v101, v88
	v_add_f32_e32 v92, v92, v102
	s_waitcnt lgkmcnt(1)
	v_add_u32_e32 v88, 0x135c0, v144
	ds_read_b128 v[88:91], v88
	v_lshlrev_b32_e32 v102, 16, v172
	v_and_b32_e32 v172, 0xffff0000, v172
	v_add_f32_e32 v93, v93, v172
	v_lshlrev_b32_e32 v172, 16, v173
	v_add_f32_e32 v94, v94, v172
	v_and_b32_e32 v172, 0xffff0000, v173
	v_add_f32_e32 v95, v95, v172
	v_lshlrev_b32_e32 v172, 16, v174
	v_add_f32_e32 v98, v98, v172
	v_and_b32_e32 v172, 0xffff0000, v174
	v_add_f32_e32 v99, v99, v172
	v_lshlrev_b32_e32 v172, 16, v175
	v_add_f32_e32 v100, v100, v172
	v_and_b32_e32 v172, 0xffff0000, v175
	v_add_f32_e32 v101, v101, v172
	v_add_f32_e32 v92, v92, v102
	s_waitcnt lgkmcnt(1)
	v_lshlrev_b32_e32 v102, 16, v168
	v_and_b32_e32 v168, 0xffff0000, v168
	v_add_f32_e32 v93, v93, v168
	v_lshlrev_b32_e32 v168, 16, v169
	v_add_f32_e32 v94, v94, v168
	v_and_b32_e32 v168, 0xffff0000, v169
	v_add_f32_e32 v95, v95, v168
	v_lshlrev_b32_e32 v168, 16, v170
	v_add_f32_e32 v98, v98, v168
	v_and_b32_e32 v168, 0xffff0000, v170
	v_add_f32_e32 v99, v99, v168
	v_lshlrev_b32_e32 v168, 16, v171
	v_add_f32_e32 v100, v100, v168
	v_and_b32_e32 v168, 0xffff0000, v171
	v_add_f32_e32 v101, v101, v168
	v_add_f32_e32 v92, v92, v102
	s_waitcnt lgkmcnt(0)
; __device__ __forceinline__ float bflo(unsigned u) { return __uint_as_float(u << 16); }
; __device__ __forceinline__ float bfhi(unsigned u) { return __uint_as_float(u & 0xffff0000u); }
; template <int W>
; __device__ __forceinline__ void pool_compute(const Params& p, int layer, int g, int dh, int tt, const int tidx) {
;     ...
;     for (int k4 = 0; k4 < 4; ++k4) {
;       const int ks = kb * 4 + k4;
;       float sum[8];
; #pragma unroll
;       for (int j = 0; j < 8; ++j) sum[j] = 0.f;
;       u32x4 x0 = *reinterpret_cast<const u32x4*>(xl + ks * 32);
; #pragma unroll
;       for (int i = 0; i < W; ++i) {
;         u32x4 xv = *reinterpret_cast<const u32x4*>(xl + ks * 32 - i * PXS);
;         sum[0] += bflo(xv.x); sum[1] += bfhi(xv.x); sum[2] += bflo(xv.y); sum[3] += bfhi(xv.y);
;         sum[4] += bflo(xv.z); sum[5] += bfhi(xv.z); sum[6] += bflo(xv.w); sum[7] += bfhi(xv.w);
;       }
;       u32x4 bfr;
;       bfr.x = pack2(sum[0] * inv - bflo(x0.x), sum[1] * inv - bfhi(x0.x));
;       bfr.y = pack2(sum[2] * inv - bflo(x0.y), sum[3] * inv - bfhi(x0.y));
;       bfr.z = pack2(sum[4] * inv - bflo(x0.z), sum[5] * inv - bfhi(x0.z));
;       bfr.w = pack2(sum[6] * inv - bflo(x0.w), sum[7] * inv - bfhi(x0.w));
; #pragma unroll
;       for (int d = 0; d < 4; ++d) acc[d] = __builtin_amdgcn_mfma_f32_32x32x16_bf16(as_bf16x8(av[k4][d]), as_bf16x8(bfr), acc[d], 0, 0, 0);
;     }
	v_lshlrev_b32_e32 v102, 16, v88
	v_and_b32_e32 v88, 0xffff0000, v88
	v_add_f32_e32 v103, v93, v88
	v_lshlrev_b32_e32 v88, 16, v89
	v_add_f32_e32 v104, v94, v88
	v_and_b32_e32 v88, 0xffff0000, v89
	v_add_f32_e32 v105, v95, v88
	v_lshlrev_b32_e32 v88, 16, v90
	v_add_f32_e32 v98, v98, v88
	v_and_b32_e32 v88, 0xffff0000, v90
	v_add_f32_e32 v99, v99, v88
	v_lshlrev_b32_e32 v88, 16, v91
	v_add_f32_e32 v100, v100, v88
	v_and_b32_e32 v88, 0xffff0000, v91
	v_add_f32_e32 v101, v101, v88
	v_add_u32_e32 v88, 0x133b0, v144
	v_add_f32_e32 v102, v92, v102
	ds_read_b128 v[92:95], v88
	s_waitcnt lgkmcnt(0)
	v_lshlrev_b32_e32 v88, 16, v92
	v_and_b32_e32 v89, 0xffff0000, v92
	v_lshlrev_b32_e32 v92, 16, v94
	v_lshlrev_b32_e32 v90, 16, v93
	v_and_b32_e32 v91, 0xffff0000, v93
	v_add_f32_e32 v92, v98, v92
	v_and_b32_e32 v93, 0xffff0000, v94
	v_lshlrev_b32_e32 v94, 16, v95
	v_and_b32_e32 v95, 0xffff0000, v95
	v_add_u32_e32 v98, 0x131a0, v144
	v_add_f32_e32 v93, v99, v93
	v_add_f32_e32 v94, v100, v94
	v_add_f32_e32 v95, v101, v95
	ds_read_b128 v[98:101], v98
	v_add_f32_e32 v88, v102, v88
	v_add_f32_e32 v89, v103, v89
	v_add_f32_e32 v90, v104, v90
	v_add_f32_e32 v91, v105, v91
	s_waitcnt lgkmcnt(0)
	v_lshlrev_b32_e32 v102, 16, v98
	v_add_f32_e32 v102, v88, v102
	v_and_b32_e32 v88, 0xffff0000, v98
	v_add_f32_e32 v98, v89, v88
	v_lshlrev_b32_e32 v88, 16, v99
	v_add_f32_e32 v103, v90, v88
	v_and_b32_e32 v88, 0xffff0000, v99
	v_add_f32_e32 v99, v91, v88
	v_lshlrev_b32_e32 v88, 16, v100
	v_add_f32_e32 v92, v92, v88
	v_and_b32_e32 v88, 0xffff0000, v100
	v_add_f32_e32 v93, v93, v88
	v_lshlrev_b32_e32 v88, 16, v101
	v_add_f32_e32 v94, v94, v88
	v_and_b32_e32 v88, 0xffff0000, v101
	v_add_f32_e32 v95, v95, v88
	v_add_u32_e32 v88, 0x12f90, v144
	ds_read_b128 v[88:91], v88
	s_waitcnt lgkmcnt(0)
	v_lshlrev_b32_e32 v100, 16, v88
	v_and_b32_e32 v88, 0xffff0000, v88
	v_add_f32_e32 v98, v98, v88
	v_lshlrev_b32_e32 v88, 16, v89
	v_add_f32_e32 v101, v103, v88
	v_and_b32_e32 v88, 0xffff0000, v89
	v_add_f32_e32 v99, v99, v88
	v_lshlrev_b32_e32 v88, 16, v90
	v_add_f32_e32 v100, v102, v100
	v_add_f32_e32 v102, v92, v88
	v_and_b32_e32 v88, 0xffff0000, v90
	v_add_f32_e32 v103, v93, v88
	v_lshlrev_b32_e32 v88, 16, v91
	v_add_f32_e32 v104, v94, v88
	v_and_b32_e32 v88, 0xffff0000, v91
	v_add_f32_e32 v105, v95, v88
	v_add_u32_e32 v88, 0x12d80, v144
	ds_read_b128 v[92:95], v88
	s_waitcnt lgkmcnt(0)
	v_and_b32_e32 v89, 0xffff0000, v92
	v_lshlrev_b32_e32 v88, 16, v92
	v_add_f32_e32 v89, v98, v89
	v_lshlrev_b32_e32 v90, 16, v93
	v_and_b32_e32 v91, 0xffff0000, v93
	v_add_u32_e32 v98, 0x12b70, v144
	v_add_f32_e32 v88, v100, v88
	v_add_f32_e32 v90, v101, v90
	v_add_f32_e32 v91, v99, v91
	ds_read_b128 v[98:101], v98
	v_lshlrev_b32_e32 v92, 16, v94
	v_add_f32_e32 v92, v102, v92
	v_and_b32_e32 v93, 0xffff0000, v94
	v_add_f32_e32 v93, v103, v93
	s_waitcnt lgkmcnt(0)
	v_lshlrev_b32_e32 v102, 16, v98
	v_add_f32_e32 v102, v88, v102
	v_and_b32_e32 v88, 0xffff0000, v98
	v_add_f32_e32 v98, v89, v88
	v_lshlrev_b32_e32 v88, 16, v99
	v_add_f32_e32 v103, v90, v88
	v_and_b32_e32 v88, 0xffff0000, v99
	v_add_f32_e32 v99, v91, v88
	v_lshlrev_b32_e32 v88, 16, v100
	v_lshlrev_b32_e32 v94, 16, v95
	v_add_f32_e32 v92, v92, v88
	v_and_b32_e32 v88, 0xffff0000, v100
	v_add_f32_e32 v94, v104, v94
	v_and_b32_e32 v95, 0xffff0000, v95
	v_add_f32_e32 v93, v93, v88
	v_lshlrev_b32_e32 v88, 16, v101
	v_add_f32_e32 v95, v105, v95
	v_add_f32_e32 v94, v94, v88
	v_and_b32_e32 v88, 0xffff0000, v101
	v_add_f32_e32 v95, v95, v88
	v_add_u32_e32 v172, 0x12960, v144
	ds_read_b128 v[172:175], v172
	s_waitcnt lgkmcnt(0)
	v_add_u32_e32 v168, 0x12750, v144
	ds_read_b128 v[168:171], v168
	v_add_u32_e32 v88, 0x12540, v144
	ds_read_b128 v[88:91], v88
	v_lshlrev_b32_e32 v100, 16, v172
	v_and_b32_e32 v172, 0xffff0000, v172
	v_add_f32_e32 v98, v98, v172
	v_lshlrev_b32_e32 v172, 16, v173
	v_add_f32_e32 v101, v103, v172
	v_and_b32_e32 v172, 0xffff0000, v173
	v_add_f32_e32 v99, v99, v172
	v_lshlrev_b32_e32 v172, 16, v174
	v_add_f32_e32 v92, v92, v172
	v_and_b32_e32 v172, 0xffff0000, v174
	v_add_f32_e32 v93, v93, v172
	v_lshlrev_b32_e32 v172, 16, v175
	v_add_f32_e32 v94, v94, v172
	v_and_b32_e32 v172, 0xffff0000, v175
	v_add_f32_e32 v95, v95, v172
	v_add_f32_e32 v100, v102, v100
	s_waitcnt lgkmcnt(1)
	v_lshlrev_b32_e32 v102, 16, v168
	v_and_b32_e32 v168, 0xffff0000, v168
	v_add_f32_e32 v98, v98, v168
	v_lshlrev_b32_e32 v168, 16, v169
	v_add_f32_e32 v101, v101, v168
	v_and_b32_e32 v168, 0xffff0000, v169
	v_add_f32_e32 v99, v99, v168
	v_lshlrev_b32_e32 v168, 16, v170
	v_add_f32_e32 v92, v92, v168
	v_and_b32_e32 v168, 0xffff0000, v170
	v_add_f32_e32 v93, v93, v168
	v_lshlrev_b32_e32 v168, 16, v171
	v_add_f32_e32 v94, v94, v168
	v_and_b32_e32 v168, 0xffff0000, v171
	v_add_f32_e32 v95, v95, v168
	v_add_f32_e32 v100, v100, v102
	s_waitcnt lgkmcnt(0)
	v_lshlrev_b32_e32 v102, 16, v88
	v_and_b32_e32 v88, 0xffff0000, v88
	v_add_f32_e32 v103, v98, v88
	v_lshlrev_b32_e32 v88, 16, v89
	v_add_f32_e32 v104, v101, v88
	v_and_b32_e32 v88, 0xffff0000, v89
	v_add_u32_e32 v89, 0x12330, v144
	v_add_f32_e32 v102, v100, v102
	v_add_f32_e32 v105, v99, v88
	ds_read_b128 v[98:101], v89
	v_lshlrev_b32_e32 v88, 16, v90
	v_add_f32_e32 v106, v92, v88
	v_and_b32_e32 v88, 0xffff0000, v90
	v_add_f32_e32 v107, v93, v88
	v_lshlrev_b32_e32 v88, 16, v91
	v_add_f32_e32 v108, v94, v88
	v_and_b32_e32 v88, 0xffff0000, v91
	s_waitcnt lgkmcnt(0)
	v_lshlrev_b32_e32 v89, 16, v98
	v_and_b32_e32 v90, 0xffff0000, v98
	v_add_f32_e32 v88, v95, v88
	v_add_f32_e32 v89, v102, v89
	v_add_f32_e32 v90, v103, v90
	v_lshlrev_b32_e32 v91, 16, v99
	v_and_b32_e32 v92, 0xffff0000, v99
	v_lshlrev_b32_e32 v93, 16, v100
	v_and_b32_e32 v94, 0xffff0000, v100
	v_lshlrev_b32_e32 v95, 16, v101
	v_and_b32_e32 v98, 0xffff0000, v101
	v_add_f32_e32 v91, v104, v91
	v_add_f32_e32 v92, v105, v92
	v_add_f32_e32 v93, v106, v93
	v_add_f32_e32 v94, v107, v94
	v_add_f32_e32 v95, v108, v95
	v_add_f32_e32 v98, v88, v98
	v_fma_f32 v86, v135, v89, -v86
	v_fma_f32 v87, v135, v90, -v87
	v_cvt_pk_bf16_f32 v86, v86, v87
	v_fma_f32 v84, v135, v91, -v84
	v_fma_f32 v85, v135, v92, -v85
	v_cvt_pk_bf16_f32 v87, v84, v85
	v_fma_f32 v83, v135, v93, -v83
	v_fma_f32 v82, v135, v94, -v82
	v_cvt_pk_bf16_f32 v88, v83, v82
	v_fma_f32 v80, v135, v95, -v80
	v_fma_f32 v81, v135, v98, -v81
	v_cvt_pk_bf16_f32 v89, v80, v81
	s_nop 0
	v_mfma_f32_32x32x16_bf16 v[48:63], v[64:67], v[86:89], v[48:63]
	v_mfma_f32_32x32x16_bf16 v[32:47], v[68:71], v[86:89], v[32:47]
	v_mfma_f32_32x32x16_bf16 v[16:31], v[72:75], v[86:89], v[16:31]
	s_waitcnt vmcnt(0)
	v_mfma_f32_32x32x16_bf16 v[0:15], v[76:79], v[86:89], v[0:15]
	s_cbranch_scc1 .LBB0_185
; #define SCHED __builtin_amdgcn_sched_barrier(0)
; template <int W>
; __device__ __forceinline__ void pool_compute(const Params& p, int layer, int g, int dh, int tt, const int tidx) {
;     ...
;   u16* yo = yraw + (size_t)t * DM + g * 256;
;   f32x4 scv[4][4];
; #pragma unroll
;   for (int d = 0; d < 4; ++d)
; #pragma unroll
;     for (int rg = 0; rg < 4; ++rg) scv[d][rg] = *reinterpret_cast<const f32x4*>(psc + (dh * 4 + d) * 32 + 8 * rg + 4 * half);
;   SCHED;
; #pragma unroll
;   for (int d = 0; d < 4; ++d)
; #pragma unroll
;     for (int rg = 0; rg < 4; ++rg) {
;       int dd = (dh * 4 + d) * 32 + 8 * rg + 4 * half;
;       f32x4 sc = scv[d][rg];
;       u32x2 o = {pack2(acc[d][rg * 4 + 0] * sc[0], acc[d][rg * 4 + 1] * sc[1]), pack2(acc[d][rg * 4 + 2] * sc[2], acc[d][rg * 4 + 3] * sc[3])};
;       *reinterpret_cast<u32x2*>(yo + dd) = o;
;     }
	v_mov_b32_e32 v135, v163
	v_lshl_add_u64 v[64:65], s[78:79], 0, v[134:135]
	v_lshlrev_b32_e32 v66, 9, v138
	v_mov_b32_e32 v67, v163
	v_lshl_add_u64 v[126:127], v[64:65], 0, v[66:67]
	global_load_dwordx4 v[64:67], v[126:127], off offset:3072
	global_load_dwordx4 v[68:71], v[126:127], off offset:3104
	global_load_dwordx4 v[72:75], v[126:127], off offset:3136
	global_load_dwordx4 v[76:79], v[126:127], off offset:3168
	global_load_dwordx4 v[80:83], v[126:127], off offset:3200
	global_load_dwordx4 v[84:87], v[126:127], off offset:3232
	global_load_dwordx4 v[88:91], v[126:127], off offset:3264
	global_load_dwordx4 v[92:95], v[126:127], off offset:3296
	global_load_dwordx4 v[98:101], v[126:127], off offset:3328
	global_load_dwordx4 v[102:105], v[126:127], off offset:3360
	global_load_dwordx4 v[106:109], v[126:127], off offset:3392
	global_load_dwordx4 v[110:113], v[126:127], off offset:3424
	global_load_dwordx4 v[114:117], v[126:127], off offset:3456
	global_load_dwordx4 v[118:121], v[126:127], off offset:3488
	global_load_dwordx4 v[122:125], v[126:127], off offset:3520
	s_nop 0
	global_load_dwordx4 v[126:129], v[126:127], off offset:3552
	v_lshlrev_b32_e32 v130, 13, v140
	v_mov_b32_e32 v131, v163
	v_lshl_add_u64 v[130:131], s[86:87], 0, v[130:131]
	s_waitcnt vmcnt(15)
	v_mul_f32_e32 v48, v48, v64
	v_mul_f32_e32 v49, v49, v65
	v_cvt_pk_bf16_f32 v64, v48, v49
	v_mul_f32_e32 v48, v50, v66
	v_mul_f32_e32 v49, v51, v67
	v_cvt_pk_bf16_f32 v65, v48, v49
	v_lshlrev_b32_e32 v48, 3, v139
	v_lshl_or_b32 v48, v138, 8, v48
	v_mov_b32_e32 v49, v163
	v_lshl_add_u64 v[50:51], v[130:131], 0, v[48:49]
	s_mov_b64 s[12:13], 0x22900600
	v_lshl_add_u64 v[48:49], v[50:51], 0, s[12:13]
	s_mov_b32 s12, 0x22900000
	s_waitcnt vmcnt(11)
	v_mul_f32_e32 v32, v32, v80
	v_mul_f32_e32 v33, v33, v81
	s_waitcnt vmcnt(7)
	v_mul_f32_e32 v16, v16, v98
	v_mul_f32_e32 v17, v17, v99
	s_waitcnt vmcnt(3)
	v_mul_f32_e32 v0, v0, v114
	v_mul_f32_e32 v1, v1, v115
	v_add_co_u32_e32 v50, vcc, s12, v50
	v_cvt_pk_bf16_f32 v32, v32, v33
	v_mul_f32_e32 v33, v34, v82
	v_cvt_pk_bf16_f32 v16, v16, v17
	v_mul_f32_e32 v17, v18, v100
	v_cvt_pk_bf16_f32 v0, v0, v1
	v_mul_f32_e32 v1, v2, v116
	v_addc_co_u32_e32 v51, vcc, 0, v51, vcc
	v_mul_f32_e32 v34, v35, v83
	v_cvt_pk_bf16_f32 v33, v33, v34
	v_mul_f32_e32 v18, v19, v101
	v_cvt_pk_bf16_f32 v17, v17, v18
	v_mul_f32_e32 v2, v3, v117
	v_cvt_pk_bf16_f32 v1, v1, v2
	global_store_dwordx2 v[50:51], v[64:65], off offset:1536
	v_mul_f32_e32 v50, v52, v68
	v_mul_f32_e32 v51, v53, v69
	global_store_dwordx2 v[48:49], v[32:33], off offset:64
	v_mul_f32_e32 v32, v36, v84
	v_mul_f32_e32 v33, v37, v85
	global_store_dwordx2 v[48:49], v[16:17], off offset:128
	v_mul_f32_e32 v16, v20, v102
	v_mul_f32_e32 v17, v21, v103
	global_store_dwordx2 v[48:49], v[0:1], off offset:192
	s_waitcnt vmcnt(6)
	v_mul_f32_e32 v0, v4, v118
	v_mul_f32_e32 v1, v5, v119
	v_cvt_pk_bf16_f32 v50, v50, v51
	v_mul_f32_e32 v51, v54, v70
	v_cvt_pk_bf16_f32 v32, v32, v33
	v_mul_f32_e32 v33, v38, v86
	v_cvt_pk_bf16_f32 v16, v16, v17
	v_mul_f32_e32 v17, v22, v104
	v_cvt_pk_bf16_f32 v0, v0, v1
	v_mul_f32_e32 v1, v6, v120
	v_mul_f32_e32 v52, v55, v71
	v_cvt_pk_bf16_f32 v51, v51, v52
	v_mul_f32_e32 v34, v39, v87
	v_cvt_pk_bf16_f32 v33, v33, v34
	v_mul_f32_e32 v18, v23, v105
	v_cvt_pk_bf16_f32 v17, v17, v18
	v_mul_f32_e32 v2, v7, v121
	v_cvt_pk_bf16_f32 v1, v1, v2
	global_store_dwordx2 v[48:49], v[50:51], off offset:16
	v_mul_f32_e32 v50, v56, v72
	v_mul_f32_e32 v51, v57, v73
	global_store_dwordx2 v[48:49], v[32:33], off offset:80
	v_mul_f32_e32 v32, v40, v88
	v_mul_f32_e32 v33, v41, v89
	global_store_dwordx2 v[48:49], v[16:17], off offset:144
	v_mul_f32_e32 v16, v24, v106
	v_mul_f32_e32 v17, v25, v107
	global_store_dwordx2 v[48:49], v[0:1], off offset:208
	s_waitcnt vmcnt(9)
	v_mul_f32_e32 v0, v8, v122
	v_mul_f32_e32 v1, v9, v123
	v_cvt_pk_bf16_f32 v50, v50, v51
	v_mul_f32_e32 v51, v58, v74
	v_cvt_pk_bf16_f32 v32, v32, v33
	v_mul_f32_e32 v33, v42, v90
	v_cvt_pk_bf16_f32 v16, v16, v17
	v_mul_f32_e32 v17, v26, v108
	v_cvt_pk_bf16_f32 v0, v0, v1
	v_mul_f32_e32 v1, v10, v124
	v_mul_f32_e32 v52, v59, v75
	v_cvt_pk_bf16_f32 v51, v51, v52
	v_mul_f32_e32 v34, v43, v91
	v_cvt_pk_bf16_f32 v33, v33, v34
	v_mul_f32_e32 v18, v27, v109
	v_cvt_pk_bf16_f32 v17, v17, v18
	v_mul_f32_e32 v2, v11, v125
	v_cvt_pk_bf16_f32 v1, v1, v2
	global_store_dwordx2 v[48:49], v[50:51], off offset:32
	v_mul_f32_e32 v50, v60, v76
	v_mul_f32_e32 v51, v61, v77
	global_store_dwordx2 v[48:49], v[32:33], off offset:96
	v_mul_f32_e32 v32, v44, v92
	v_mul_f32_e32 v33, v45, v93
	global_store_dwordx2 v[48:49], v[16:17], off offset:160
	v_mul_f32_e32 v16, v28, v110
	v_mul_f32_e32 v17, v29, v111
	global_store_dwordx2 v[48:49], v[0:1], off offset:224
	s_waitcnt vmcnt(12)
	v_mul_f32_e32 v0, v12, v126
	v_mul_f32_e32 v1, v13, v127
	v_cvt_pk_bf16_f32 v50, v50, v51
	v_mul_f32_e32 v51, v62, v78
	v_cvt_pk_bf16_f32 v32, v32, v33
	v_mul_f32_e32 v33, v46, v94
	v_cvt_pk_bf16_f32 v16, v16, v17
	v_mul_f32_e32 v17, v30, v112
	v_cvt_pk_bf16_f32 v0, v0, v1
	v_mul_f32_e32 v1, v14, v128
	s_andn2_b64 s[8:9], s[8:9], exec
	v_mul_f32_e32 v52, v63, v79
	v_cvt_pk_bf16_f32 v51, v51, v52
	global_store_dwordx2 v[48:49], v[50:51], off offset:48
	v_mul_f32_e32 v34, v47, v95
	v_cvt_pk_bf16_f32 v33, v33, v34
	global_store_dwordx2 v[48:49], v[32:33], off offset:112
	v_mul_f32_e32 v18, v31, v113
	v_cvt_pk_bf16_f32 v17, v17, v18
	global_store_dwordx2 v[48:49], v[16:17], off offset:176
	v_mul_f32_e32 v2, v15, v129
	v_cvt_pk_bf16_f32 v1, v1, v2
	s_setprio 0
	s_or_b64 exec, exec, s[10:11]
	s_and_saveexec_b64 s[10:11], s[8:9]
	s_xor_b64 s[8:9], exec, s[10:11]
	s_cbranch_execz .LBB0_190
